# KIND0 tile loop unrolled by the 3 ring slots: per-slot K/V fragment-read addresses formed once per unit, five vector adds per tile removed
# speedup vs baseline: 1.0132x; 1.0059x over previous
; DI int otid() { int t = threadIdx.x; asm volatile("" : "+v"(t)); return t; }
; DI int crow(int reg, int h) { return (reg & 3) + 8 * (reg >> 2) + 4 * h; }
; template <int KIND>
; DI void attn_unit(const Params& p, int l, int b, int head, int qt, int qcol, int kcol, int vfeat, int gcol, int mixcol,
;                   int t1, int n1, int t2, int n2, char* smem) {
;     const int tid = otid(), lane = tid & 63, wave = tid >> 6, r = lane & 31, h = lane >> 5;
;     const int tq = qt * 128 + 32 * wave + r;
;     const size_t qrow = (size_t)b * TPB + tq;
;     const bf16_t* kbase = p.qkv + ((size_t)(kcol >> 6) * NTOK + (size_t)b * TPB) * 64;
;     const bf16_t* vbase = p.vT + ((size_t)b * 12 + (vfeat >> 6)) * 36 * 4096;
;     const int nt = n1 + n2;
;     bf16x8 qf[4];
;     {
;         const bf16_t* qp = p.qkv + ((size_t)(qcol >> 6) * NTOK + qrow) * 64 + 8 * h;
; #pragma unroll
;         for (int s = 0; s < 4; ++s) qf[s] = *(const bf16x8*)(qp + 16 * s);
;     }
;     int nrow = 0, r0w = 0, qc = 0, c0 = 0;
;     if (KIND == 2) {
;         nrow = 2 * qt + (wave >> 1); r0w = min(max(nrow - 4, 0), 24);
;         qc = 32 * (wave & 1) + r; c0 = min(max(qc - 8, 0), 48);
;         float* bias = (float*)(smem + ATT_BIAS);
;         for (int i = tid; i < 15 * 32; i += NTHREADS) { const int rr = i >> 5, cc = i & 31; bias[i] = cc < 31 ? p.rpb[((size_t)l * 6 + head) * 465 + rr * 31 + cc] * LOG2E : -INFINITY; }
;     }
;     int bcol[2][16];
;     if (KIND == 2) {
; #pragma unroll
;         for (int t = 0; t < 2; ++t)
; #pragma unroll
;             for (int e = 0; e < 16; ++e) {
;                 const int kc = 32 * t + crow(e, h);
;                 bcol[t][e] = ((unsigned)(kc - c0) < 16u) ? (kc - qc + 15) * 4 : 31 * 4;
;             }
;     }
;     f32x16 O0[2], O1[2];
; #pragma unroll
;     for (int t = 0; t < 2; ++t)
; #pragma unroll
;         for (int e = 0; e < 16; ++e) { O0[t][e] = 0.f; O1[t][e] = 0.f; }
;     float l0 = 0.f, l1 = 0.f;
;     const float zb = p.lam[8 + l * 4 + ((KIND == 1 && qcol >= 2048) ? 3 : KIND)];
;     f32x16 cz;
; #pragma unroll
;     for (int e = 0; e < 16; ++e) cz[e] = -zb;
;     const int kvoff = (8 * wave + (lane >> 3)) * 64 + (((lane & 7) ^ (((wave & 1) << 2) | (lane >> 4))) << 3);
;     const int xr = (r >> 1) & 7;
;     __syncthreads();
;     KV_ISSUE(t1, 0);
;     if (nt > 1) KV_ISSUE((1 < n1) ? t1 + 1 : t2 + (1 - n1), 1);
.LBB0_81:
	s_and_b32 s6, s8, 3
	s_mul_i32 s8, s6, 0x4800
	s_lshl_b32 s7, s7, 7
	s_mul_i32 s29, s35, 0x900
	s_add_i32 s5, s8, 0x12000
	s_mul_hi_i32 s9, s35, 0x900
	s_add_u32 s56, s29, s5
	s_mul_i32 s34, s35, 12
	v_mov_b32_e32 v23, v200
	s_addc_u32 s57, s9, 0
	s_mul_hi_i32 s5, s35, 12
	s_or_b32 s34, s34, s6
	s_load_dwordx4 s[40:43], s[0:1], 0xc0
	s_load_dwordx2 s[50:51], s[0:1], 0xf8
	v_ashrrev_i32_e32 v16, 6, v23
	s_mul_i32 s53, s34, 0x48000
	s_mul_hi_u32 s34, s34, 0x48000
	s_mul_i32 s5, s5, 0x48000
	v_and_b32_e32 v22, 31, v23
	v_lshl_add_u32 v0, v16, 5, s7
	s_lshl_b64 s[56:57], s[56:57], 7
	s_add_i32 s5, s34, s5
	v_or_b32_e32 v0, v0, v22
	s_add_u32 s58, s29, s8
	v_ashrrev_i32_e32 v1, 31, v0
	s_addc_u32 s59, s9, 0
	v_lshl_add_u64 v[0:1], s[58:59], 0, v[0:1]
	s_waitcnt lgkmcnt(0)
	s_add_u32 s58, s40, s56
	v_bfe_u32 v214, v23, 5, 1
	v_lshlrev_b64 v[0:1], 7, v[0:1]
	s_addc_u32 s59, s41, s57
	s_lshl_b64 s[56:57], s[48:49], 2
	v_lshl_add_u64 v[0:1], s[40:41], 0, v[0:1]
	v_lshlrev_b32_e32 v192, 4, v214
	s_add_u32 s56, s50, s56
	v_lshl_add_u64 v[0:1], v[0:1], 0, v[192:193]
	s_addc_u32 s57, s51, s57
	global_load_dwordx4 v[152:155], v[0:1], off
	global_load_dwordx4 v[144:147], v[0:1], off offset:32
	global_load_dwordx4 v[156:159], v[0:1], off offset:64
	global_load_dwordx4 v[148:151], v[0:1], off offset:96
	v_lshlrev_b32_e32 v17, 9, v16
	global_load_dword v0, v193, s[56:57] offset:32
	v_lshlrev_b32_e32 v18, 3, v23
	s_movk_i32 s56, 0x1c0
	v_lshlrev_b32_e32 v16, 2, v16
	v_and_or_b32 v17, v18, s56, v17
	v_and_b32_e32 v18, 7, v23
	v_and_b32_e32 v16, 4, v16
	v_bfe_u32 v19, v23, 4, 2
	s_add_u32 s53, s42, s53
	v_bitop3_b32 v16, v16, v18, v19 bitop3:0x36
	s_addc_u32 s5, s43, s5
	v_lshl_or_b32 v16, v16, 3, v17
	s_lshl_b32 s4, s4, 13
	s_add_u32 s56, s58, s4
	v_ashrrev_i32_e32 v17, 31, v16
	s_addc_u32 s57, s59, 0
	v_lshlrev_b64 v[16:17], 1, v[16:17]
	v_lshl_add_u64 v[20:21], s[56:57], 0, v[16:17]
	s_add_u32 s56, s53, s4
	v_lshl_add_u32 v220, v23, 4, 32
	v_lshrrev_b32_e32 v28, 1, v23
	v_bfe_u32 v29, v23, 1, 3
	s_addc_u32 s57, s5, 0
	v_readfirstlane_b32 s5, v220
	v_add_u32_e32 v23, 0x1000, v220
	s_mov_b32 m0, s5
	v_readfirstlane_b32 s5, v23
	v_add_u32_e32 v23, 0x2000, v220
	s_barrier
	global_load_lds_dwordx4 v[20:21], off
	v_lshl_add_u64 v[24:25], v[20:21], 0, s[26:27]
	s_mov_b32 m0, s5
	v_readfirstlane_b32 s5, v23
	v_add_u32_e32 v23, 0x3000, v220
	v_lshl_add_u64 v[18:19], s[56:57], 0, v[16:17]
	global_load_lds_dwordx4 v[24:25], off
	s_mov_b32 m0, s5
	v_readfirstlane_b32 s5, v23
	v_add_u32_e32 v23, 0x4000, v220
	global_load_lds_dwordx4 v[18:19], off
	v_lshl_add_u64 v[24:25], v[18:19], 0, s[26:27]
	s_mov_b32 m0, s5
	v_readfirstlane_b32 s5, v23
	v_add_u32_e32 v23, 0x5000, v220
	global_load_lds_dwordx4 v[24:25], off
	v_lshl_add_u64 v[24:25], v[20:21], 0, s[16:17]
	s_mov_b32 m0, s5
	v_readfirstlane_b32 s5, v23
	global_load_lds_dwordx4 v[24:25], off
	v_lshl_add_u64 v[20:21], v[20:21], 0, s[90:91]
	s_mov_b32 m0, s5
	v_lshl_add_u64 v[26:27], v[18:19], 0, s[16:17]
	global_load_lds_dwordx4 v[20:21], off
	v_add_u32_e32 v20, 0x6000, v220
	v_lshl_add_u64 v[18:19], v[18:19], 0, s[90:91]
	v_readfirstlane_b32 s5, v20
	v_add_u32_e32 v20, 0x7000, v220
	s_mov_b32 m0, s5
	v_readfirstlane_b32 s5, v20
	global_load_lds_dwordx4 v[26:27], off
	s_mov_b32 m0, s5
	s_lshl_b32 s5, s52, 13
	global_load_lds_dwordx4 v[18:19], off
	s_add_u32 s52, s5, 0x2000
	s_mul_i32 s53, s35, 0x360000
	s_mul_i32 s56, s6, 0x48000
	s_mul_hi_i32 s5, s35, 0x360000
	s_add_u32 s53, s53, s56
	s_addc_u32 s5, s5, 0
	s_add_u32 s53, s53, s4
	s_addc_u32 s5, s5, 0
	s_add_u32 s42, s42, s53
	s_addc_u32 s43, s43, s5
	v_lshl_add_u64 v[196:197], s[42:43], 0, v[16:17]
	s_add_u32 s98, s42, 0x4000
	s_addc_u32 s99, s43, 0
	s_mul_i32 s5, s6, 0x240000
	s_mul_hi_i32 s42, s35, 0x48000
	s_mul_i32 s35, s35, 0x48000
	s_add_u32 s5, s5, s35
	s_addc_u32 s35, 0, s42
	s_add_u32 s4, s5, s4
	v_bitop3_b32 v18, v214, v28, 7 bitop3:0x78
	s_addc_u32 s5, s35, 0
	v_lshlrev_b32_e32 v219, 4, v18
	v_bitop3_b32 v18, v214, v29, 2 bitop3:0x36
	s_add_u32 s4, s40, s4
	v_lshlrev_b32_e32 v218, 4, v18
	v_bitop3_b32 v18, v214, v29, 4 bitop3:0x36
	s_addc_u32 s5, s41, s5
	s_waitcnt vmcnt(0)
	v_xor_b32_e32 v0, 0x80000000, v0
	v_lshlrev_b32_e32 v217, 7, v22
	v_lshlrev_b32_e32 v216, 4, v18
	v_bitop3_b32 v18, v214, v29, 6 bitop3:0x36
	v_lshl_add_u64 v[198:199], s[4:5], 0, v[16:17]
	s_add_u32 s62, s4, 0x904000
	s_addc_u32 s63, s5, 0
	v_mov_b32_e32 v226, v16
	v_add_u32_e32 v227, 0x1000, v16
	v_mov_b32_e32 v16, 0
	s_mov_b32 s34, 2
	v_mov_b32_e32 v1, v0
	v_mov_b32_e32 v2, v0
	v_mov_b32_e32 v3, v0
	v_mov_b32_e32 v4, v0
	v_mov_b32_e32 v5, v0
	v_mov_b32_e32 v6, v0
	v_mov_b32_e32 v7, v0
	v_mov_b32_e32 v8, v0
	v_mov_b32_e32 v9, v0
	v_mov_b32_e32 v10, v0
	v_mov_b32_e32 v11, v0
	v_mov_b32_e32 v12, v0
	v_mov_b32_e32 v13, v0
	v_mov_b32_e32 v14, v0
	v_mov_b32_e32 v15, v0
	v_lshlrev_b32_e32 v215, 4, v18
	v_add_u32_e32 v221, 32, v217
	s_mov_b32 s35, 0
	s_mov_b64 s[4:5], 0
	v_mov_b32_e32 v17, v16
	v_mov_b32_e32 v18, v16
	v_mov_b32_e32 v19, v16
	v_mov_b32_e32 v20, v16
	v_mov_b32_e32 v21, v16
	v_mov_b32_e32 v22, v16
	v_mov_b32_e32 v23, v16
	v_mov_b32_e32 v24, v16
	v_mov_b32_e32 v25, v16
	v_mov_b32_e32 v26, v16
	v_mov_b32_e32 v27, v16
	v_mov_b32_e32 v28, v16
	v_mov_b32_e32 v29, v16
	v_mov_b32_e32 v30, v16
	v_mov_b32_e32 v31, v16
	v_mov_b32_e32 v48, v16
	v_mov_b32_e32 v49, v16
	v_mov_b32_e32 v50, v16
	v_mov_b32_e32 v51, v16
	v_mov_b32_e32 v52, v16
	v_mov_b32_e32 v53, v16
	v_mov_b32_e32 v54, v16
	v_mov_b32_e32 v55, v16
	v_mov_b32_e32 v56, v16
	v_mov_b32_e32 v57, v16
	v_mov_b32_e32 v58, v16
	v_mov_b32_e32 v59, v16
	v_mov_b32_e32 v60, v16
	v_mov_b32_e32 v61, v16
	v_mov_b32_e32 v62, v16
; #define MFMA(a, b, c) __builtin_amdgcn_mfma_f32_32x32x16_bf16((a), (b), (c), 0, 0, 0)
; template <int KIND>
; DI void attn_unit(const Params& p, int l, int b, int head, int qt, int qcol, int kcol, int vfeat, int gcol, int mixcol,
;                   int t1, int n1, int t2, int n2, char* smem) {
;     ...
;     f32x16 O0[2], O1[2];
; #pragma unroll
;     for (int t = 0; t < 2; ++t)
; #pragma unroll
;         for (int e = 0; e < 16; ++e) { O0[t][e] = 0.f; O1[t][e] = 0.f; }
;     float l0 = 0.f, l1 = 0.f;
;     const float zb = p.lam[8 + l * 4 + ((KIND == 1 && qcol >= 2048) ? 3 : KIND)];
;     f32x16 cz;
; #pragma unroll
;     for (int e = 0; e < 16; ++e) cz[e] = -zb;
;     const int kvoff = (8 * wave + (lane >> 3)) * 64 + (((lane & 7) ^ (((wave & 1) << 2) | (lane >> 4))) << 3);
;     const int xr = (r >> 1) & 7;
;     ...
;     for (int it = 0; it < nt; ++it) {
;         const int tile = (it < n1) ? t1 + it : t2 + (it - n1);
;         if (it + 1 < nt) asm volatile("s_waitcnt vmcnt(4)" ::: "memory"); else asm volatile("s_waitcnt vmcnt(0)" ::: "memory");
;         __builtin_amdgcn_s_barrier();
;         const char* sk = smem + sc * ATT_SLOT;
;         const char* sv = sk + ATT_V;
;         bool active = true;
;         if (KIND == 2 && tile < 32) active = (tile >= r0w) && (tile < r0w + 8);
;         bf16x8 kf[8], vf[8];
;         if (active) {
; #pragma unroll
;             for (int s = 0; s < 4; ++s)
; #pragma unroll
;                 for (int t = 0; t < 2; ++t) kf[2 * s + t] = *(const bf16x8*)(sk + (32 * t + r) * 128 + (((2 * s + h) ^ xr) << 4));
;         }
;         __builtin_amdgcn_sched_barrier(0);
;         if (it + 2 < nt) { const int nx = (it + 2 < n1) ? t1 + it + 2 : t2 + (it + 2 - n1); KV_ISSUE(nx, sn); }
;         sc = (sc == 2) ? 0 : sc + 1; sn = (sn == 2) ? 0 : sn + 1;
;         __builtin_amdgcn_sched_barrier(0);
;         if (active) {
;     ...
;             if (KIND == 0) {
;                 f32x16 S0[2], S1[2];
; #pragma unroll
;                 for (int t = 0; t < 2; ++t) { S0[t] = MFMA(kf[t], qf[0], cz); S1[t] = MFMA(kf[4 + t], qf[2], cz); }
; #pragma unroll
;                 for (int t = 0; t < 2; ++t) { S0[t] = MFMA(kf[2 + t], qf[1], S0[t]); S1[t] = MFMA(kf[6 + t], qf[3], S1[t]); }
;                 LOAD_VF();
;                 softmax_tile(S0, l0);
;                 pv_tile(S0, O0, vf);
;                 softmax_tile(S1, l1);
;                 pv_tile(S1, O1, vf);
	v_mov_b32_e32 v63, v16
	v_mov_b32_e32 v32, v16
	v_mov_b32_e32 v33, v16
	v_mov_b32_e32 v34, v16
	v_mov_b32_e32 v35, v16
	v_mov_b32_e32 v36, v16
	v_mov_b32_e32 v37, v16
	v_mov_b32_e32 v38, v16
	v_mov_b32_e32 v39, v16
	v_mov_b32_e32 v40, v16
	v_mov_b32_e32 v41, v16
	v_mov_b32_e32 v42, v16
	v_mov_b32_e32 v43, v16
	v_mov_b32_e32 v44, v16
	v_mov_b32_e32 v45, v16
	v_mov_b32_e32 v46, v16
	v_mov_b32_e32 v47, v16
	v_mov_b32_e32 v64, v16
	v_mov_b32_e32 v65, v16
	v_mov_b32_e32 v66, v16
	v_mov_b32_e32 v67, v16
	v_mov_b32_e32 v68, v16
	v_mov_b32_e32 v69, v16
	v_mov_b32_e32 v70, v16
	v_mov_b32_e32 v71, v16
	v_mov_b32_e32 v72, v16
	v_mov_b32_e32 v73, v16
	v_mov_b32_e32 v74, v16
	v_mov_b32_e32 v75, v16
	v_mov_b32_e32 v76, v16
	v_mov_b32_e32 v77, v16
	v_mov_b32_e32 v78, v16
	v_mov_b32_e32 v79, v16
	v_mov_b32_e32 v194, v16
	v_mov_b32_e32 v195, v16
	v_readfirstlane_b32 s100, v220
	v_mov_b32_e32 v80, 0
	v_mov_b32_e32 v81, 0
	v_mov_b32_e32 v82, 0
	v_mov_b32_e32 v83, 0
	v_mov_b32_e32 v84, 0
	v_mov_b32_e32 v85, 0
	v_mov_b32_e32 v86, 0
	v_mov_b32_e32 v87, 0
	v_mov_b32_e32 v88, 0
	v_mov_b32_e32 v89, 0
	v_mov_b32_e32 v90, 0
	v_mov_b32_e32 v91, 0
	v_mov_b32_e32 v92, 0
	v_mov_b32_e32 v93, 0
	v_mov_b32_e32 v94, 0
	v_mov_b32_e32 v95, 0
	v_mov_b32_e32 v96, 0
	v_mov_b32_e32 v97, 0
	v_mov_b32_e32 v98, 0
	v_mov_b32_e32 v99, 0
	v_mov_b32_e32 v100, 0
	v_mov_b32_e32 v101, 0
	v_mov_b32_e32 v102, 0
	v_mov_b32_e32 v103, 0
	v_mov_b32_e32 v104, 0
	v_mov_b32_e32 v105, 0
	v_mov_b32_e32 v106, 0
	v_mov_b32_e32 v107, 0
	v_mov_b32_e32 v108, 0
	v_mov_b32_e32 v109, 0
	v_mov_b32_e32 v110, 0
	v_mov_b32_e32 v111, 0
	v_mov_b32_e32 v160, 0
	v_mov_b32_e32 v161, 0
	v_mov_b32_e32 v162, 0
	v_mov_b32_e32 v163, 0
	v_mov_b32_e32 v164, 0
	v_mov_b32_e32 v165, 0
	v_mov_b32_e32 v166, 0
	v_mov_b32_e32 v167, 0
	v_mov_b32_e32 v168, 0
	v_mov_b32_e32 v169, 0
	v_mov_b32_e32 v170, 0
	v_mov_b32_e32 v171, 0
	v_mov_b32_e32 v172, 0
	v_mov_b32_e32 v173, 0
	v_mov_b32_e32 v174, 0
	v_mov_b32_e32 v175, 0
	v_mov_b32_e32 v176, 0
	v_mov_b32_e32 v177, 0
	v_mov_b32_e32 v178, 0
	v_mov_b32_e32 v179, 0
	v_mov_b32_e32 v180, 0
	v_mov_b32_e32 v181, 0
	v_mov_b32_e32 v182, 0
	v_mov_b32_e32 v183, 0
	v_mov_b32_e32 v184, 0
	v_mov_b32_e32 v185, 0
	v_mov_b32_e32 v186, 0
	v_mov_b32_e32 v187, 0
	v_mov_b32_e32 v188, 0
	v_mov_b32_e32 v189, 0
	v_mov_b32_e32 v190, 0
	v_mov_b32_e32 v191, 0
	v_mov_b32_e32 v252, 0
	v_mov_b32_e32 v253, 0
	v_add_u32_e32 v222, v221, v218
	v_add_u32_e32 v223, v221, v216
	v_add_u32_e32 v224, v221, v215
	v_add_u32_e32 v225, v221, v219
	v_add_u32_e32 v197, v221, v218
	v_add_u32_e32 v198, v221, v216
	v_add_u32_e32 v199, v221, v215
	v_add_u32_e32 v196, v221, v219
	v_add_u32_e32 v197, 0x4000, v197
	v_add_u32_e32 v198, 0x4000, v198
	v_add_u32_e32 v199, 0x4000, v199
	v_add_u32_e32 v196, 0x4000, v196
	v_add_u32_e32 v229, v221, v218
	v_add_u32_e32 v230, v221, v216
	v_add_u32_e32 v231, v221, v215
	v_add_u32_e32 v228, v221, v219
	v_add_u32_e32 v229, 0x8000, v229
	v_add_u32_e32 v230, 0x8000, v230
	v_add_u32_e32 v231, 0x8000, v231
	v_add_u32_e32 v228, 0x8000, v228
.LBB0_82:
	s_waitcnt vmcnt(4)
	s_barrier
	ds_read_b128 v[234:237], v225
	ds_read_b128 v[238:241], v225 offset:4096
	ds_read_b128 v[242:245], v222
	ds_read_b128 v[246:249], v222 offset:4096
	s_lshl_b32 s101, s34, 14
	s_add_i32 s101, s101, s100
	s_add_i32 s42, s35, 1
	s_cmp_lg_u32 s35, 2
	s_cselect_b32 s35, s42, 0
	s_add_i32 s42, s34, 1
	v_add_f32_e32 v252, v80, v252
	v_add_f32_e32 v253, v81, v253
	v_cvt_pk_bf16_f32 v80, v80, v81
	v_add_f32_e32 v252, v82, v252
	v_add_f32_e32 v253, v83, v253
	v_cvt_pk_bf16_f32 v81, v82, v83
	v_add_f32_e32 v252, v84, v252
	v_add_f32_e32 v253, v85, v253
	v_cvt_pk_bf16_f32 v82, v84, v85
	v_add_f32_e32 v252, v86, v252
	v_add_f32_e32 v253, v87, v253
	v_cvt_pk_bf16_f32 v83, v86, v87
	s_mov_b32 m0, s101
	s_waitcnt lgkmcnt(0)
	v_mfma_f32_32x32x16_bf16 v[128:143], v[234:237], v[152:155], v[0:15]
	global_load_lds_dwordx4 v226, s[62:63]
	s_add_u32 m0, s101, 0x1000
	v_add_f32_e32 v252, v88, v252
	v_add_f32_e32 v253, v89, v253
	v_cvt_pk_bf16_f32 v88, v88, v89
	v_mfma_f32_32x32x16_bf16 v[112:127], v[238:241], v[152:155], v[0:15]
	global_load_lds_dwordx4 v227, s[62:63]
	s_add_u32 m0, s101, 0x2000
	v_add_f32_e32 v252, v90, v252
	v_add_f32_e32 v253, v91, v253
	v_cvt_pk_bf16_f32 v89, v90, v91
	v_mfma_f32_32x32x16_bf16 v[128:143], v[242:245], v[144:147], v[128:143]
	global_load_lds_dwordx4 v226, s[98:99]
	s_add_u32 m0, s101, 0x3000
	v_add_f32_e32 v252, v92, v252
	v_add_f32_e32 v253, v93, v253
	v_cvt_pk_bf16_f32 v90, v92, v93
	v_mfma_f32_32x32x16_bf16 v[112:127], v[246:249], v[144:147], v[112:127]
	global_load_lds_dwordx4 v227, s[98:99]
	v_add_f32_e32 v252, v94, v252
	v_add_f32_e32 v253, v95, v253
	v_cvt_pk_bf16_f32 v91, v94, v95
	v_add_f32_e32 v252, v252, v253
	v_add_f32_e32 v194, v194, v252
	s_cmp_lg_u32 s34, 2
	s_cselect_b32 s34, s42, 0
	s_add_u32 s62, s62, 0x2000
	s_addc_u32 s63, s63, 0
	s_add_u32 s98, s98, 0x2000
	s_addc_u32 s99, s99, 0
	ds_read_b128 v[234:237], v223
	ds_read_b128 v[238:241], v223 offset:4096
	ds_read_b128 v[242:245], v224
	ds_read_b128 v[246:249], v224 offset:4096
	v_mfma_f32_32x32x16_bf16 v[64:79], v[188:191], v[96:99], v[64:79]
	v_exp_f32_e32 v128, v128
	v_exp_f32_e32 v129, v129
	v_exp_f32_e32 v130, v130
	v_exp_f32_e32 v131, v131
	v_mfma_f32_32x32x16_bf16 v[16:31], v[184:187], v[96:99], v[16:31]
	v_exp_f32_e32 v132, v132
	v_exp_f32_e32 v133, v133
	v_exp_f32_e32 v134, v134
	v_exp_f32_e32 v135, v135
	v_mfma_f32_32x32x16_bf16 v[64:79], v[180:183], v[104:107], v[64:79]
	v_exp_f32_e32 v136, v136
	v_exp_f32_e32 v137, v137
	v_exp_f32_e32 v138, v138
	v_exp_f32_e32 v139, v139
	v_add_f32_e64 v250, v128, 0
	v_add_f32_e64 v251, v129, 0
; #define MFMA(a, b, c) __builtin_amdgcn_mfma_f32_32x32x16_bf16((a), (b), (c), 0, 0, 0)
; #define LOAD_VF() do { \
;             __builtin_amdgcn_sched_barrier(0); \
;             _Pragma("unroll") for (int s = 0; s < 4; ++s) \
;                 _Pragma("unroll") for (int dt = 0; dt < 2; ++dt) vf[2 * s + dt] = ldv_frag(sv, 32 * dt + r, 2 * s + h, xr); \
;             __builtin_amdgcn_sched_barrier(0); } while (0)
; DI void softmax_tile(f32x16 (&S)[2], float& lsum) {
;     f2_t ps = {0.f, 0.f};
; #pragma unroll
;     for (int t = 0; t < 2; ++t)
; #pragma unroll
;         for (int e = 0; e < 16; e += 2) {
;             f2_t pv; pv.x = __builtin_amdgcn_exp2f(S[t][e]); pv.y = __builtin_amdgcn_exp2f(S[t][e + 1]);
;             S[t][e] = pv.x; S[t][e + 1] = pv.y;
;             ps += pv;
;         }
;     lsum += ps.x + ps.y;
; }
; DI void pv_tile(const f32x16 (&S)[2], f32x16 (&O)[2], const bf16x8 (&vf)[8]) {
; #pragma unroll
;     for (int s = 0; s < 4; ++s) {
;         const bf16x8 pf = pack8(S[s >> 1], s & 1);
; #pragma unroll
;         for (int dt = 0; dt < 2; ++dt) O[dt] = MFMA(vf[2 * s + dt], pf, O[dt]);
;     }
; }
; template <int KIND>
; DI void attn_unit(const Params& p, int l, int b, int head, int qt, int qcol, int kcol, int vfeat, int gcol, int mixcol,
;                   int t1, int n1, int t2, int n2, char* smem) {
;     ...
;             if (KIND == 0) {
;                 f32x16 S0[2], S1[2];
; #pragma unroll
;                 for (int t = 0; t < 2; ++t) { S0[t] = MFMA(kf[t], qf[0], cz); S1[t] = MFMA(kf[4 + t], qf[2], cz); }
; #pragma unroll
;                 for (int t = 0; t < 2; ++t) { S0[t] = MFMA(kf[2 + t], qf[1], S0[t]); S1[t] = MFMA(kf[6 + t], qf[3], S1[t]); }
;                 LOAD_VF();
;                 softmax_tile(S0, l0);
;                 pv_tile(S0, O0, vf);
;                 softmax_tile(S1, l1);
;                 pv_tile(S1, O1, vf);
	v_cvt_pk_bf16_f32 v128, v128, v129
	v_add_f32_e32 v250, v130, v250
	v_add_f32_e32 v251, v131, v251
	v_cvt_pk_bf16_f32 v129, v130, v131
	v_mfma_f32_32x32x16_bf16 v[16:31], v[176:179], v[104:107], v[16:31]
	v_exp_f32_e32 v140, v140
	v_exp_f32_e32 v141, v141
	v_exp_f32_e32 v142, v142
	v_exp_f32_e32 v143, v143
	v_add_f32_e32 v250, v132, v250
	v_add_f32_e32 v251, v133, v251
	v_cvt_pk_bf16_f32 v130, v132, v133
	v_add_f32_e32 v250, v134, v250
	v_add_f32_e32 v251, v135, v251
	v_cvt_pk_bf16_f32 v131, v134, v135
	v_mfma_f32_32x32x16_bf16 v[64:79], v[172:175], v[80:83], v[64:79]
	v_exp_f32_e32 v112, v112
	v_exp_f32_e32 v113, v113
	v_exp_f32_e32 v114, v114
	v_exp_f32_e32 v115, v115
	v_add_f32_e32 v250, v136, v250
	v_add_f32_e32 v251, v137, v251
	v_cvt_pk_bf16_f32 v136, v136, v137
	v_add_f32_e32 v250, v138, v250
	v_add_f32_e32 v251, v139, v251
	v_cvt_pk_bf16_f32 v137, v138, v139
	v_mfma_f32_32x32x16_bf16 v[16:31], v[168:171], v[80:83], v[16:31]
	v_exp_f32_e32 v116, v116
	v_exp_f32_e32 v117, v117
	v_exp_f32_e32 v118, v118
	v_exp_f32_e32 v119, v119
	v_add_f32_e32 v250, v140, v250
	v_add_f32_e32 v251, v141, v251
	v_cvt_pk_bf16_f32 v138, v140, v141
	v_add_f32_e32 v250, v142, v250
	v_add_f32_e32 v251, v143, v251
	v_cvt_pk_bf16_f32 v139, v142, v143
	v_mfma_f32_32x32x16_bf16 v[64:79], v[164:167], v[88:91], v[64:79]
	v_exp_f32_e32 v120, v120
	v_exp_f32_e32 v121, v121
	v_exp_f32_e32 v122, v122
	v_exp_f32_e32 v123, v123
	v_mfma_f32_32x32x16_bf16 v[16:31], v[160:163], v[88:91], v[16:31]
	v_exp_f32_e32 v124, v124
	v_exp_f32_e32 v125, v125
	v_exp_f32_e32 v126, v126
	v_exp_f32_e32 v127, v127
	s_waitcnt lgkmcnt(0)
	ds_read_b128 v[188:191], v225 offset:8192
	ds_read_b128 v[184:187], v225 offset:12288
	ds_read_b128 v[180:183], v222 offset:8192
	ds_read_b128 v[176:179], v222 offset:12288
	ds_read_b128 v[172:175], v223 offset:8192
	ds_read_b128 v[168:171], v223 offset:12288
	ds_read_b128 v[164:167], v224 offset:8192
	ds_read_b128 v[160:163], v224 offset:12288
	v_mfma_f32_32x32x16_bf16 v[96:111], v[234:237], v[156:159], v[0:15]
	v_add_f32_e32 v250, v112, v250
	v_add_f32_e32 v251, v113, v251
	v_cvt_pk_bf16_f32 v112, v112, v113
	v_add_f32_e32 v250, v114, v250
	v_add_f32_e32 v251, v115, v251
	v_cvt_pk_bf16_f32 v113, v114, v115
	v_mfma_f32_32x32x16_bf16 v[80:95], v[238:241], v[156:159], v[0:15]
	v_add_f32_e32 v250, v116, v250
	v_add_f32_e32 v251, v117, v251
	v_cvt_pk_bf16_f32 v114, v116, v117
	v_add_f32_e32 v250, v118, v250
	v_add_f32_e32 v251, v119, v251
	v_cvt_pk_bf16_f32 v115, v118, v119
	v_mfma_f32_32x32x16_bf16 v[96:111], v[242:245], v[148:151], v[96:111]
	v_add_f32_e32 v250, v120, v250
	v_add_f32_e32 v251, v121, v251
	v_cvt_pk_bf16_f32 v120, v120, v121
	v_add_f32_e32 v250, v122, v250
	v_add_f32_e32 v251, v123, v251
	v_cvt_pk_bf16_f32 v121, v122, v123
	v_mfma_f32_32x32x16_bf16 v[80:95], v[246:249], v[148:151], v[80:95]
	v_add_f32_e32 v250, v124, v250
	v_add_f32_e32 v251, v125, v251
	v_cvt_pk_bf16_f32 v122, v124, v125
	v_add_f32_e32 v250, v126, v250
	v_add_f32_e32 v251, v127, v251
	v_cvt_pk_bf16_f32 v123, v126, v127
	v_add_f32_e32 v250, v250, v251
	v_add_f32_e32 v195, v195, v250
	s_add_u32 s4, s4, 0x2000
	s_addc_u32 s5, s5, 0
	s_waitcnt lgkmcnt(0)
	v_mfma_f32_32x32x16_bf16 v[48:63], v[188:191], v[128:131], v[48:63]
	v_exp_f32_e32 v96, v96
	v_exp_f32_e32 v97, v97
	v_exp_f32_e32 v98, v98
	v_exp_f32_e32 v99, v99
	v_mfma_f32_32x32x16_bf16 v[32:47], v[184:187], v[128:131], v[32:47]
	v_exp_f32_e32 v100, v100
	v_exp_f32_e32 v101, v101
	v_exp_f32_e32 v102, v102
	v_exp_f32_e32 v103, v103
	v_mfma_f32_32x32x16_bf16 v[48:63], v[180:183], v[136:139], v[48:63]
	v_exp_f32_e32 v104, v104
	v_exp_f32_e32 v105, v105
	v_exp_f32_e32 v106, v106
	v_exp_f32_e32 v107, v107
	v_add_f32_e64 v252, v96, 0
	v_add_f32_e64 v253, v97, 0
	v_cvt_pk_bf16_f32 v96, v96, v97
	v_add_f32_e32 v252, v98, v252
	v_add_f32_e32 v253, v99, v253
	v_cvt_pk_bf16_f32 v97, v98, v99
	v_mfma_f32_32x32x16_bf16 v[32:47], v[176:179], v[136:139], v[32:47]
	v_exp_f32_e32 v108, v108
	v_exp_f32_e32 v109, v109
	v_exp_f32_e32 v110, v110
	v_exp_f32_e32 v111, v111
	v_add_f32_e32 v252, v100, v252
	v_add_f32_e32 v253, v101, v253
	v_cvt_pk_bf16_f32 v98, v100, v101
	v_add_f32_e32 v252, v102, v252
	v_add_f32_e32 v253, v103, v253
	v_cvt_pk_bf16_f32 v99, v102, v103
	v_mfma_f32_32x32x16_bf16 v[48:63], v[172:175], v[112:115], v[48:63]
	v_exp_f32_e32 v80, v80
	v_exp_f32_e32 v81, v81
	v_exp_f32_e32 v82, v82
	v_exp_f32_e32 v83, v83
	v_add_f32_e32 v252, v104, v252
	v_add_f32_e32 v253, v105, v253
	v_cvt_pk_bf16_f32 v104, v104, v105
	v_add_f32_e32 v252, v106, v252
	v_add_f32_e32 v253, v107, v253
	v_cvt_pk_bf16_f32 v105, v106, v107
	v_mfma_f32_32x32x16_bf16 v[32:47], v[168:171], v[112:115], v[32:47]
	v_exp_f32_e32 v84, v84
	v_exp_f32_e32 v85, v85
	v_exp_f32_e32 v86, v86
	v_exp_f32_e32 v87, v87
	v_add_f32_e32 v252, v108, v252
	v_add_f32_e32 v253, v109, v253
	v_cvt_pk_bf16_f32 v106, v108, v109
	v_add_f32_e32 v252, v110, v252
	v_add_f32_e32 v253, v111, v253
	v_cvt_pk_bf16_f32 v107, v110, v111
	v_mfma_f32_32x32x16_bf16 v[48:63], v[164:167], v[120:123], v[48:63]
	v_exp_f32_e32 v88, v88
	v_exp_f32_e32 v89, v89
	v_exp_f32_e32 v90, v90
	v_exp_f32_e32 v91, v91
	v_mfma_f32_32x32x16_bf16 v[32:47], v[160:163], v[120:123], v[32:47]
	v_exp_f32_e32 v92, v92
	v_exp_f32_e32 v93, v93
	v_exp_f32_e32 v94, v94
	v_exp_f32_e32 v95, v95
	s_cmp_eq_u32 s52, s4
	s_cbranch_scc1 .Lk0u_exit
	s_waitcnt vmcnt(4)
	s_barrier
; DI void softmax_tile(f32x16 (&S)[2], float& lsum) {
;     f2_t ps = {0.f, 0.f};
; #pragma unroll
;     for (int t = 0; t < 2; ++t)
; #pragma unroll
;         for (int e = 0; e < 16; e += 2) {
;             f2_t pv; pv.x = __builtin_amdgcn_exp2f(S[t][e]); pv.y = __builtin_amdgcn_exp2f(S[t][e + 1]);
;             S[t][e] = pv.x; S[t][e + 1] = pv.y;
;             ps += pv;
;         }
;     lsum += ps.x + ps.y;
; }
; DI void pv_tile(const f32x16 (&S)[2], f32x16 (&O)[2], const bf16x8 (&vf)[8]) {
; #pragma unroll
;     for (int s = 0; s < 4; ++s) {
;         const bf16x8 pf = pack8(S[s >> 1], s & 1);
; template <int KIND>
; DI void attn_unit(const Params& p, int l, int b, int head, int qt, int qcol, int kcol, int vfeat, int gcol, int mixcol,
;                   int t1, int n1, int t2, int n2, char* smem) {
;     ...
;     for (int it = 0; it < nt; ++it) {
;         const int tile = (it < n1) ? t1 + it : t2 + (it - n1);
;         if (it + 1 < nt) asm volatile("s_waitcnt vmcnt(4)" ::: "memory"); else asm volatile("s_waitcnt vmcnt(0)" ::: "memory");
;         __builtin_amdgcn_s_barrier();
;         const char* sk = smem + sc * ATT_SLOT;
;         const char* sv = sk + ATT_V;
;         bool active = true;
;         if (KIND == 2 && tile < 32) active = (tile >= r0w) && (tile < r0w + 8);
;         bf16x8 kf[8], vf[8];
;         if (active) {
; #pragma unroll
;             for (int s = 0; s < 4; ++s)
; #pragma unroll
;                 for (int t = 0; t < 2; ++t) kf[2 * s + t] = *(const bf16x8*)(sk + (32 * t + r) * 128 + (((2 * s + h) ^ xr) << 4));
;         }
;         __builtin_amdgcn_sched_barrier(0);
;         if (it + 2 < nt) { const int nx = (it + 2 < n1) ? t1 + it + 2 : t2 + (it + 2 - n1); KV_ISSUE(nx, sn); }
;         sc = (sc == 2) ? 0 : sc + 1; sn = (sn == 2) ? 0 : sn + 1;
;         __builtin_amdgcn_sched_barrier(0);
;         if (active) {
;     ...
;             if (KIND == 0) {
;                 f32x16 S0[2], S1[2];
; #pragma unroll
;                 for (int t = 0; t < 2; ++t) { S0[t] = MFMA(kf[t], qf[0], cz); S1[t] = MFMA(kf[4 + t], qf[2], cz); }
; #pragma unroll
;                 for (int t = 0; t < 2; ++t) { S0[t] = MFMA(kf[2 + t], qf[1], S0[t]); S1[t] = MFMA(kf[6 + t], qf[3], S1[t]); }
;                 LOAD_VF();
;                 softmax_tile(S0, l0);
;                 pv_tile(S0, O0, vf);
;                 softmax_tile(S1, l1);
;                 pv_tile(S1, O1, vf);
	ds_read_b128 v[234:237], v196
	ds_read_b128 v[238:241], v196 offset:4096
	ds_read_b128 v[242:245], v197
	ds_read_b128 v[246:249], v197 offset:4096
	s_lshl_b32 s101, s34, 14
	s_add_i32 s101, s101, s100
	s_add_i32 s42, s35, 1
	s_cmp_lg_u32 s35, 2
	s_cselect_b32 s35, s42, 0
	s_add_i32 s42, s34, 1
	v_add_f32_e32 v252, v80, v252
	v_add_f32_e32 v253, v81, v253
	v_cvt_pk_bf16_f32 v80, v80, v81
	v_add_f32_e32 v252, v82, v252
	v_add_f32_e32 v253, v83, v253
	v_cvt_pk_bf16_f32 v81, v82, v83
	v_add_f32_e32 v252, v84, v252
	v_add_f32_e32 v253, v85, v253
	v_cvt_pk_bf16_f32 v82, v84, v85
	v_add_f32_e32 v252, v86, v252
	v_add_f32_e32 v253, v87, v253
	v_cvt_pk_bf16_f32 v83, v86, v87
	s_mov_b32 m0, s101
	s_waitcnt lgkmcnt(0)
	v_mfma_f32_32x32x16_bf16 v[128:143], v[234:237], v[152:155], v[0:15]
	global_load_lds_dwordx4 v226, s[62:63]
	s_add_u32 m0, s101, 0x1000
	v_add_f32_e32 v252, v88, v252
	v_add_f32_e32 v253, v89, v253
	v_cvt_pk_bf16_f32 v88, v88, v89
	v_mfma_f32_32x32x16_bf16 v[112:127], v[238:241], v[152:155], v[0:15]
	global_load_lds_dwordx4 v227, s[62:63]
	s_add_u32 m0, s101, 0x2000
	v_add_f32_e32 v252, v90, v252
	v_add_f32_e32 v253, v91, v253
	v_cvt_pk_bf16_f32 v89, v90, v91
	v_mfma_f32_32x32x16_bf16 v[128:143], v[242:245], v[144:147], v[128:143]
	global_load_lds_dwordx4 v226, s[98:99]
	s_add_u32 m0, s101, 0x3000
	v_add_f32_e32 v252, v92, v252
	v_add_f32_e32 v253, v93, v253
	v_cvt_pk_bf16_f32 v90, v92, v93
	v_mfma_f32_32x32x16_bf16 v[112:127], v[246:249], v[144:147], v[112:127]
	global_load_lds_dwordx4 v227, s[98:99]
	v_add_f32_e32 v252, v94, v252
	v_add_f32_e32 v253, v95, v253
	v_cvt_pk_bf16_f32 v91, v94, v95
	v_add_f32_e32 v252, v252, v253
	v_add_f32_e32 v194, v194, v252
	s_cmp_lg_u32 s34, 2
	s_cselect_b32 s34, s42, 0
	s_add_u32 s62, s62, 0x2000
	s_addc_u32 s63, s63, 0
	s_add_u32 s98, s98, 0x2000
	s_addc_u32 s99, s99, 0
	ds_read_b128 v[234:237], v198
	ds_read_b128 v[238:241], v198 offset:4096
	ds_read_b128 v[242:245], v199
	ds_read_b128 v[246:249], v199 offset:4096
	v_mfma_f32_32x32x16_bf16 v[64:79], v[188:191], v[96:99], v[64:79]
	v_exp_f32_e32 v128, v128
	v_exp_f32_e32 v129, v129
	v_exp_f32_e32 v130, v130
	v_exp_f32_e32 v131, v131
	v_mfma_f32_32x32x16_bf16 v[16:31], v[184:187], v[96:99], v[16:31]
	v_exp_f32_e32 v132, v132
	v_exp_f32_e32 v133, v133
	v_exp_f32_e32 v134, v134
	v_exp_f32_e32 v135, v135
	v_mfma_f32_32x32x16_bf16 v[64:79], v[180:183], v[104:107], v[64:79]
	v_exp_f32_e32 v136, v136
	v_exp_f32_e32 v137, v137
	v_exp_f32_e32 v138, v138
	v_exp_f32_e32 v139, v139
	v_add_f32_e64 v250, v128, 0
	v_add_f32_e64 v251, v129, 0
	v_cvt_pk_bf16_f32 v128, v128, v129
	v_add_f32_e32 v250, v130, v250
	v_add_f32_e32 v251, v131, v251
	v_cvt_pk_bf16_f32 v129, v130, v131
	v_mfma_f32_32x32x16_bf16 v[16:31], v[176:179], v[104:107], v[16:31]
	v_exp_f32_e32 v140, v140
	v_exp_f32_e32 v141, v141
	v_exp_f32_e32 v142, v142
	v_exp_f32_e32 v143, v143
	v_add_f32_e32 v250, v132, v250
	v_add_f32_e32 v251, v133, v251
	v_cvt_pk_bf16_f32 v130, v132, v133
	v_add_f32_e32 v250, v134, v250
	v_add_f32_e32 v251, v135, v251
	v_cvt_pk_bf16_f32 v131, v134, v135
	v_mfma_f32_32x32x16_bf16 v[64:79], v[172:175], v[80:83], v[64:79]
	v_exp_f32_e32 v112, v112
	v_exp_f32_e32 v113, v113
	v_exp_f32_e32 v114, v114
	v_exp_f32_e32 v115, v115
	v_add_f32_e32 v250, v136, v250
	v_add_f32_e32 v251, v137, v251
	v_cvt_pk_bf16_f32 v136, v136, v137
	v_add_f32_e32 v250, v138, v250
	v_add_f32_e32 v251, v139, v251
	v_cvt_pk_bf16_f32 v137, v138, v139
	v_mfma_f32_32x32x16_bf16 v[16:31], v[168:171], v[80:83], v[16:31]
	v_exp_f32_e32 v116, v116
	v_exp_f32_e32 v117, v117
	v_exp_f32_e32 v118, v118
	v_exp_f32_e32 v119, v119
	v_add_f32_e32 v250, v140, v250
	v_add_f32_e32 v251, v141, v251
	v_cvt_pk_bf16_f32 v138, v140, v141
	v_add_f32_e32 v250, v142, v250
	v_add_f32_e32 v251, v143, v251
	v_cvt_pk_bf16_f32 v139, v142, v143
	v_mfma_f32_32x32x16_bf16 v[64:79], v[164:167], v[88:91], v[64:79]
	v_exp_f32_e32 v120, v120
	v_exp_f32_e32 v121, v121
	v_exp_f32_e32 v122, v122
	v_exp_f32_e32 v123, v123
	v_mfma_f32_32x32x16_bf16 v[16:31], v[160:163], v[88:91], v[16:31]
	v_exp_f32_e32 v124, v124
	v_exp_f32_e32 v125, v125
	v_exp_f32_e32 v126, v126
	v_exp_f32_e32 v127, v127
	s_waitcnt lgkmcnt(0)
	ds_read_b128 v[188:191], v196 offset:8192
	ds_read_b128 v[184:187], v196 offset:12288
	ds_read_b128 v[180:183], v197 offset:8192
	ds_read_b128 v[176:179], v197 offset:12288
	ds_read_b128 v[172:175], v198 offset:8192
	ds_read_b128 v[168:171], v198 offset:12288
	ds_read_b128 v[164:167], v199 offset:8192
	ds_read_b128 v[160:163], v199 offset:12288
	v_mfma_f32_32x32x16_bf16 v[96:111], v[234:237], v[156:159], v[0:15]
	v_add_f32_e32 v250, v112, v250
	v_add_f32_e32 v251, v113, v251
	v_cvt_pk_bf16_f32 v112, v112, v113
	v_add_f32_e32 v250, v114, v250
	v_add_f32_e32 v251, v115, v251
	v_cvt_pk_bf16_f32 v113, v114, v115
	v_mfma_f32_32x32x16_bf16 v[80:95], v[238:241], v[156:159], v[0:15]
	v_add_f32_e32 v250, v116, v250
	v_add_f32_e32 v251, v117, v251
	v_cvt_pk_bf16_f32 v114, v116, v117
	v_add_f32_e32 v250, v118, v250
	v_add_f32_e32 v251, v119, v251
	v_cvt_pk_bf16_f32 v115, v118, v119
	v_mfma_f32_32x32x16_bf16 v[96:111], v[242:245], v[148:151], v[96:111]
	v_add_f32_e32 v250, v120, v250
	v_add_f32_e32 v251, v121, v251
	v_cvt_pk_bf16_f32 v120, v120, v121
	v_add_f32_e32 v250, v122, v250
	v_add_f32_e32 v251, v123, v251
	v_cvt_pk_bf16_f32 v121, v122, v123
	v_mfma_f32_32x32x16_bf16 v[80:95], v[246:249], v[148:151], v[80:95]
	v_add_f32_e32 v250, v124, v250
	v_add_f32_e32 v251, v125, v251
	v_cvt_pk_bf16_f32 v122, v124, v125
	v_add_f32_e32 v250, v126, v250
	v_add_f32_e32 v251, v127, v251
	v_cvt_pk_bf16_f32 v123, v126, v127
	v_add_f32_e32 v250, v250, v251
	v_add_f32_e32 v195, v195, v250
	s_add_u32 s4, s4, 0x2000
	s_addc_u32 s5, s5, 0
	s_waitcnt lgkmcnt(0)
; DI void softmax_tile(f32x16 (&S)[2], float& lsum) {
;     f2_t ps = {0.f, 0.f};
; #pragma unroll
;     for (int t = 0; t < 2; ++t)
; #pragma unroll
;         for (int e = 0; e < 16; e += 2) {
;             f2_t pv; pv.x = __builtin_amdgcn_exp2f(S[t][e]); pv.y = __builtin_amdgcn_exp2f(S[t][e + 1]);
;             S[t][e] = pv.x; S[t][e + 1] = pv.y;
;             ps += pv;
;         }
;     lsum += ps.x + ps.y;
; }
; DI void pv_tile(const f32x16 (&S)[2], f32x16 (&O)[2], const bf16x8 (&vf)[8]) {
; #pragma unroll
;     for (int s = 0; s < 4; ++s) {
;         const bf16x8 pf = pack8(S[s >> 1], s & 1);
; #pragma unroll
;         for (int dt = 0; dt < 2; ++dt) O[dt] = MFMA(vf[2 * s + dt], pf, O[dt]);
;     }
; }
; template <int KIND>
; DI void attn_unit(const Params& p, int l, int b, int head, int qt, int qcol, int kcol, int vfeat, int gcol, int mixcol,
;                   int t1, int n1, int t2, int n2, char* smem) {
;     ...
;     for (int it = 0; it < nt; ++it) {
;         const int tile = (it < n1) ? t1 + it : t2 + (it - n1);
;         if (it + 1 < nt) asm volatile("s_waitcnt vmcnt(4)" ::: "memory"); else asm volatile("s_waitcnt vmcnt(0)" ::: "memory");
;         __builtin_amdgcn_s_barrier();
;         const char* sk = smem + sc * ATT_SLOT;
;         const char* sv = sk + ATT_V;
;         bool active = true;
;         if (KIND == 2 && tile < 32) active = (tile >= r0w) && (tile < r0w + 8);
;         bf16x8 kf[8], vf[8];
;         if (active) {
; #pragma unroll
;             for (int s = 0; s < 4; ++s)
; #pragma unroll
;                 for (int t = 0; t < 2; ++t) kf[2 * s + t] = *(const bf16x8*)(sk + (32 * t + r) * 128 + (((2 * s + h) ^ xr) << 4));
;         }
;         __builtin_amdgcn_sched_barrier(0);
;         if (it + 2 < nt) { const int nx = (it + 2 < n1) ? t1 + it + 2 : t2 + (it + 2 - n1); KV_ISSUE(nx, sn); }
;         sc = (sc == 2) ? 0 : sc + 1; sn = (sn == 2) ? 0 : sn + 1;
;         __builtin_amdgcn_sched_barrier(0);
;         if (active) {
;     ...
;             if (KIND == 0) {
;                 f32x16 S0[2], S1[2];
; #pragma unroll
;                 for (int t = 0; t < 2; ++t) { S0[t] = MFMA(kf[t], qf[0], cz); S1[t] = MFMA(kf[4 + t], qf[2], cz); }
; #pragma unroll
;                 for (int t = 0; t < 2; ++t) { S0[t] = MFMA(kf[2 + t], qf[1], S0[t]); S1[t] = MFMA(kf[6 + t], qf[3], S1[t]); }
;                 LOAD_VF();
;                 softmax_tile(S0, l0);
	v_mfma_f32_32x32x16_bf16 v[48:63], v[188:191], v[128:131], v[48:63]
	v_exp_f32_e32 v96, v96
	v_exp_f32_e32 v97, v97
	v_exp_f32_e32 v98, v98
	v_exp_f32_e32 v99, v99
	v_mfma_f32_32x32x16_bf16 v[32:47], v[184:187], v[128:131], v[32:47]
	v_exp_f32_e32 v100, v100
	v_exp_f32_e32 v101, v101
	v_exp_f32_e32 v102, v102
	v_exp_f32_e32 v103, v103
	v_mfma_f32_32x32x16_bf16 v[48:63], v[180:183], v[136:139], v[48:63]
	v_exp_f32_e32 v104, v104
	v_exp_f32_e32 v105, v105
	v_exp_f32_e32 v106, v106
	v_exp_f32_e32 v107, v107
	v_add_f32_e64 v252, v96, 0
	v_add_f32_e64 v253, v97, 0
	v_cvt_pk_bf16_f32 v96, v96, v97
	v_add_f32_e32 v252, v98, v252
	v_add_f32_e32 v253, v99, v253
	v_cvt_pk_bf16_f32 v97, v98, v99
	v_mfma_f32_32x32x16_bf16 v[32:47], v[176:179], v[136:139], v[32:47]
	v_exp_f32_e32 v108, v108
	v_exp_f32_e32 v109, v109
	v_exp_f32_e32 v110, v110
	v_exp_f32_e32 v111, v111
	v_add_f32_e32 v252, v100, v252
	v_add_f32_e32 v253, v101, v253
	v_cvt_pk_bf16_f32 v98, v100, v101
	v_add_f32_e32 v252, v102, v252
	v_add_f32_e32 v253, v103, v253
	v_cvt_pk_bf16_f32 v99, v102, v103
	v_mfma_f32_32x32x16_bf16 v[48:63], v[172:175], v[112:115], v[48:63]
	v_exp_f32_e32 v80, v80
	v_exp_f32_e32 v81, v81
	v_exp_f32_e32 v82, v82
	v_exp_f32_e32 v83, v83
	v_add_f32_e32 v252, v104, v252
	v_add_f32_e32 v253, v105, v253
	v_cvt_pk_bf16_f32 v104, v104, v105
	v_add_f32_e32 v252, v106, v252
	v_add_f32_e32 v253, v107, v253
	v_cvt_pk_bf16_f32 v105, v106, v107
	v_mfma_f32_32x32x16_bf16 v[32:47], v[168:171], v[112:115], v[32:47]
	v_exp_f32_e32 v84, v84
	v_exp_f32_e32 v85, v85
	v_exp_f32_e32 v86, v86
	v_exp_f32_e32 v87, v87
	v_add_f32_e32 v252, v108, v252
	v_add_f32_e32 v253, v109, v253
	v_cvt_pk_bf16_f32 v106, v108, v109
	v_add_f32_e32 v252, v110, v252
	v_add_f32_e32 v253, v111, v253
	v_cvt_pk_bf16_f32 v107, v110, v111
	v_mfma_f32_32x32x16_bf16 v[48:63], v[164:167], v[120:123], v[48:63]
	v_exp_f32_e32 v88, v88
	v_exp_f32_e32 v89, v89
	v_exp_f32_e32 v90, v90
	v_exp_f32_e32 v91, v91
	v_mfma_f32_32x32x16_bf16 v[32:47], v[160:163], v[120:123], v[32:47]
	v_exp_f32_e32 v92, v92
	v_exp_f32_e32 v93, v93
	v_exp_f32_e32 v94, v94
	v_exp_f32_e32 v95, v95
	s_cmp_eq_u32 s52, s4
	s_cbranch_scc1 .Lk0u_exit
	s_waitcnt vmcnt(4)
	s_barrier
	ds_read_b128 v[234:237], v228
	ds_read_b128 v[238:241], v228 offset:4096
	ds_read_b128 v[242:245], v229
	ds_read_b128 v[246:249], v229 offset:4096
	s_lshl_b32 s101, s34, 14
	s_add_i32 s101, s101, s100
	s_add_i32 s42, s35, 1
	s_cmp_lg_u32 s35, 2
	s_cselect_b32 s35, s42, 0
	s_add_i32 s42, s34, 1
	v_add_f32_e32 v252, v80, v252
	v_add_f32_e32 v253, v81, v253
	v_cvt_pk_bf16_f32 v80, v80, v81
	v_add_f32_e32 v252, v82, v252
	v_add_f32_e32 v253, v83, v253
	v_cvt_pk_bf16_f32 v81, v82, v83
	v_add_f32_e32 v252, v84, v252
	v_add_f32_e32 v253, v85, v253
	v_cvt_pk_bf16_f32 v82, v84, v85
	v_add_f32_e32 v252, v86, v252
	v_add_f32_e32 v253, v87, v253
	v_cvt_pk_bf16_f32 v83, v86, v87
	s_mov_b32 m0, s101
	s_waitcnt lgkmcnt(0)
	v_mfma_f32_32x32x16_bf16 v[128:143], v[234:237], v[152:155], v[0:15]
	global_load_lds_dwordx4 v226, s[62:63]
	s_add_u32 m0, s101, 0x1000
	v_add_f32_e32 v252, v88, v252
	v_add_f32_e32 v253, v89, v253
	v_cvt_pk_bf16_f32 v88, v88, v89
	v_mfma_f32_32x32x16_bf16 v[112:127], v[238:241], v[152:155], v[0:15]
	global_load_lds_dwordx4 v227, s[62:63]
	s_add_u32 m0, s101, 0x2000
	v_add_f32_e32 v252, v90, v252
	v_add_f32_e32 v253, v91, v253
	v_cvt_pk_bf16_f32 v89, v90, v91
	v_mfma_f32_32x32x16_bf16 v[128:143], v[242:245], v[144:147], v[128:143]
	global_load_lds_dwordx4 v226, s[98:99]
	s_add_u32 m0, s101, 0x3000
	v_add_f32_e32 v252, v92, v252
	v_add_f32_e32 v253, v93, v253
	v_cvt_pk_bf16_f32 v90, v92, v93
	v_mfma_f32_32x32x16_bf16 v[112:127], v[246:249], v[144:147], v[112:127]
	global_load_lds_dwordx4 v227, s[98:99]
	v_add_f32_e32 v252, v94, v252
	v_add_f32_e32 v253, v95, v253
	v_cvt_pk_bf16_f32 v91, v94, v95
	v_add_f32_e32 v252, v252, v253
	v_add_f32_e32 v194, v194, v252
	s_cmp_lg_u32 s34, 2
	s_cselect_b32 s34, s42, 0
	s_add_u32 s62, s62, 0x2000
	s_addc_u32 s63, s63, 0
	s_add_u32 s98, s98, 0x2000
	s_addc_u32 s99, s99, 0
	ds_read_b128 v[234:237], v230
	ds_read_b128 v[238:241], v230 offset:4096
	ds_read_b128 v[242:245], v231
	ds_read_b128 v[246:249], v231 offset:4096
	v_mfma_f32_32x32x16_bf16 v[64:79], v[188:191], v[96:99], v[64:79]
	v_exp_f32_e32 v128, v128
	v_exp_f32_e32 v129, v129
	v_exp_f32_e32 v130, v130
	v_exp_f32_e32 v131, v131
	v_mfma_f32_32x32x16_bf16 v[16:31], v[184:187], v[96:99], v[16:31]
	v_exp_f32_e32 v132, v132
	v_exp_f32_e32 v133, v133
	v_exp_f32_e32 v134, v134
	v_exp_f32_e32 v135, v135
	v_mfma_f32_32x32x16_bf16 v[64:79], v[180:183], v[104:107], v[64:79]
	v_exp_f32_e32 v136, v136
	v_exp_f32_e32 v137, v137
	v_exp_f32_e32 v138, v138
	v_exp_f32_e32 v139, v139
	v_add_f32_e64 v250, v128, 0
	v_add_f32_e64 v251, v129, 0
	v_cvt_pk_bf16_f32 v128, v128, v129
	v_add_f32_e32 v250, v130, v250
	v_add_f32_e32 v251, v131, v251
	v_cvt_pk_bf16_f32 v129, v130, v131
	v_mfma_f32_32x32x16_bf16 v[16:31], v[176:179], v[104:107], v[16:31]
	v_exp_f32_e32 v140, v140
	v_exp_f32_e32 v141, v141
	v_exp_f32_e32 v142, v142
	v_exp_f32_e32 v143, v143
	v_add_f32_e32 v250, v132, v250
	v_add_f32_e32 v251, v133, v251
	v_cvt_pk_bf16_f32 v130, v132, v133
	v_add_f32_e32 v250, v134, v250
	v_add_f32_e32 v251, v135, v251
	v_cvt_pk_bf16_f32 v131, v134, v135
	v_mfma_f32_32x32x16_bf16 v[64:79], v[172:175], v[80:83], v[64:79]
	v_exp_f32_e32 v112, v112
	v_exp_f32_e32 v113, v113
	v_exp_f32_e32 v114, v114
	v_exp_f32_e32 v115, v115
	v_add_f32_e32 v250, v136, v250
	v_add_f32_e32 v251, v137, v251
	v_cvt_pk_bf16_f32 v136, v136, v137
	v_add_f32_e32 v250, v138, v250
	v_add_f32_e32 v251, v139, v251
	v_cvt_pk_bf16_f32 v137, v138, v139
	v_mfma_f32_32x32x16_bf16 v[16:31], v[168:171], v[80:83], v[16:31]
	v_exp_f32_e32 v116, v116
	v_exp_f32_e32 v117, v117
	v_exp_f32_e32 v118, v118
	v_exp_f32_e32 v119, v119
	v_add_f32_e32 v250, v140, v250
	v_add_f32_e32 v251, v141, v251
	v_cvt_pk_bf16_f32 v138, v140, v141
	v_add_f32_e32 v250, v142, v250
	v_add_f32_e32 v251, v143, v251
	v_cvt_pk_bf16_f32 v139, v142, v143
	v_mfma_f32_32x32x16_bf16 v[64:79], v[164:167], v[88:91], v[64:79]
	v_exp_f32_e32 v120, v120
	v_exp_f32_e32 v121, v121
	v_exp_f32_e32 v122, v122
	v_exp_f32_e32 v123, v123
	v_mfma_f32_32x32x16_bf16 v[16:31], v[160:163], v[88:91], v[16:31]
	v_exp_f32_e32 v124, v124
	v_exp_f32_e32 v125, v125
	v_exp_f32_e32 v126, v126
	v_exp_f32_e32 v127, v127
	s_waitcnt lgkmcnt(0)
; DI void softmax_tile(f32x16 (&S)[2], float& lsum) {
;     f2_t ps = {0.f, 0.f};
; #pragma unroll
;     for (int t = 0; t < 2; ++t)
; #pragma unroll
;         for (int e = 0; e < 16; e += 2) {
;             f2_t pv; pv.x = __builtin_amdgcn_exp2f(S[t][e]); pv.y = __builtin_amdgcn_exp2f(S[t][e + 1]);
;             S[t][e] = pv.x; S[t][e + 1] = pv.y;
;             ps += pv;
;         }
;     lsum += ps.x + ps.y;
; }
; DI void pv_tile(const f32x16 (&S)[2], f32x16 (&O)[2], const bf16x8 (&vf)[8]) {
; #pragma unroll
;     for (int s = 0; s < 4; ++s) {
;         const bf16x8 pf = pack8(S[s >> 1], s & 1);
; #pragma unroll
;         for (int dt = 0; dt < 2; ++dt) O[dt] = MFMA(vf[2 * s + dt], pf, O[dt]);
;     }
; }
; template <int KIND>
; DI void attn_unit(const Params& p, int l, int b, int head, int qt, int qcol, int kcol, int vfeat, int gcol, int mixcol,
;                   int t1, int n1, int t2, int n2, char* smem) {
;     ...
;     for (int it = 0; it < nt; ++it) {
;         const int tile = (it < n1) ? t1 + it : t2 + (it - n1);
;         if (it + 1 < nt) asm volatile("s_waitcnt vmcnt(4)" ::: "memory"); else asm volatile("s_waitcnt vmcnt(0)" ::: "memory");
;         __builtin_amdgcn_s_barrier();
;         const char* sk = smem + sc * ATT_SLOT;
;         const char* sv = sk + ATT_V;
;         bool active = true;
;         if (KIND == 2 && tile < 32) active = (tile >= r0w) && (tile < r0w + 8);
;         bf16x8 kf[8], vf[8];
;         if (active) {
; #pragma unroll
;             for (int s = 0; s < 4; ++s)
; #pragma unroll
;                 for (int t = 0; t < 2; ++t) kf[2 * s + t] = *(const bf16x8*)(sk + (32 * t + r) * 128 + (((2 * s + h) ^ xr) << 4));
;         }
;         __builtin_amdgcn_sched_barrier(0);
;         if (it + 2 < nt) { const int nx = (it + 2 < n1) ? t1 + it + 2 : t2 + (it + 2 - n1); KV_ISSUE(nx, sn); }
;         sc = (sc == 2) ? 0 : sc + 1; sn = (sn == 2) ? 0 : sn + 1;
;         __builtin_amdgcn_sched_barrier(0);
;         if (active) {
;     ...
;             if (KIND == 0) {
;                 f32x16 S0[2], S1[2];
; #pragma unroll
;                 for (int t = 0; t < 2; ++t) { S0[t] = MFMA(kf[t], qf[0], cz); S1[t] = MFMA(kf[4 + t], qf[2], cz); }
; #pragma unroll
;                 for (int t = 0; t < 2; ++t) { S0[t] = MFMA(kf[2 + t], qf[1], S0[t]); S1[t] = MFMA(kf[6 + t], qf[3], S1[t]); }
;                 LOAD_VF();
;                 softmax_tile(S0, l0);
	ds_read_b128 v[188:191], v228 offset:8192
	ds_read_b128 v[184:187], v228 offset:12288
	ds_read_b128 v[180:183], v229 offset:8192
	ds_read_b128 v[176:179], v229 offset:12288
	ds_read_b128 v[172:175], v230 offset:8192
	ds_read_b128 v[168:171], v230 offset:12288
	ds_read_b128 v[164:167], v231 offset:8192
	ds_read_b128 v[160:163], v231 offset:12288
	v_mfma_f32_32x32x16_bf16 v[96:111], v[234:237], v[156:159], v[0:15]
	v_add_f32_e32 v250, v112, v250
	v_add_f32_e32 v251, v113, v251
	v_cvt_pk_bf16_f32 v112, v112, v113
	v_add_f32_e32 v250, v114, v250
	v_add_f32_e32 v251, v115, v251
	v_cvt_pk_bf16_f32 v113, v114, v115
	v_mfma_f32_32x32x16_bf16 v[80:95], v[238:241], v[156:159], v[0:15]
	v_add_f32_e32 v250, v116, v250
	v_add_f32_e32 v251, v117, v251
	v_cvt_pk_bf16_f32 v114, v116, v117
	v_add_f32_e32 v250, v118, v250
	v_add_f32_e32 v251, v119, v251
	v_cvt_pk_bf16_f32 v115, v118, v119
	v_mfma_f32_32x32x16_bf16 v[96:111], v[242:245], v[148:151], v[96:111]
	v_add_f32_e32 v250, v120, v250
	v_add_f32_e32 v251, v121, v251
	v_cvt_pk_bf16_f32 v120, v120, v121
	v_add_f32_e32 v250, v122, v250
	v_add_f32_e32 v251, v123, v251
	v_cvt_pk_bf16_f32 v121, v122, v123
	v_mfma_f32_32x32x16_bf16 v[80:95], v[246:249], v[148:151], v[80:95]
	v_add_f32_e32 v250, v124, v250
	v_add_f32_e32 v251, v125, v251
	v_cvt_pk_bf16_f32 v122, v124, v125
	v_add_f32_e32 v250, v126, v250
	v_add_f32_e32 v251, v127, v251
	v_cvt_pk_bf16_f32 v123, v126, v127
	v_add_f32_e32 v250, v250, v251
	v_add_f32_e32 v195, v195, v250
	s_add_u32 s4, s4, 0x2000
	s_addc_u32 s5, s5, 0
	s_waitcnt lgkmcnt(0)
	v_mfma_f32_32x32x16_bf16 v[48:63], v[188:191], v[128:131], v[48:63]
	v_exp_f32_e32 v96, v96
	v_exp_f32_e32 v97, v97
	v_exp_f32_e32 v98, v98
	v_exp_f32_e32 v99, v99
	v_mfma_f32_32x32x16_bf16 v[32:47], v[184:187], v[128:131], v[32:47]
	v_exp_f32_e32 v100, v100
	v_exp_f32_e32 v101, v101
	v_exp_f32_e32 v102, v102
	v_exp_f32_e32 v103, v103
	v_mfma_f32_32x32x16_bf16 v[48:63], v[180:183], v[136:139], v[48:63]
	v_exp_f32_e32 v104, v104
	v_exp_f32_e32 v105, v105
	v_exp_f32_e32 v106, v106
	v_exp_f32_e32 v107, v107
	v_add_f32_e64 v252, v96, 0
	v_add_f32_e64 v253, v97, 0
	v_cvt_pk_bf16_f32 v96, v96, v97
	v_add_f32_e32 v252, v98, v252
	v_add_f32_e32 v253, v99, v253
	v_cvt_pk_bf16_f32 v97, v98, v99
	v_mfma_f32_32x32x16_bf16 v[32:47], v[176:179], v[136:139], v[32:47]
	v_exp_f32_e32 v108, v108
	v_exp_f32_e32 v109, v109
	v_exp_f32_e32 v110, v110
	v_exp_f32_e32 v111, v111
	v_add_f32_e32 v252, v100, v252
	v_add_f32_e32 v253, v101, v253
	v_cvt_pk_bf16_f32 v98, v100, v101
	v_add_f32_e32 v252, v102, v252
	v_add_f32_e32 v253, v103, v253
	v_cvt_pk_bf16_f32 v99, v102, v103
	v_mfma_f32_32x32x16_bf16 v[48:63], v[172:175], v[112:115], v[48:63]
	v_exp_f32_e32 v80, v80
	v_exp_f32_e32 v81, v81
	v_exp_f32_e32 v82, v82
	v_exp_f32_e32 v83, v83
	v_add_f32_e32 v252, v104, v252
	v_add_f32_e32 v253, v105, v253
	v_cvt_pk_bf16_f32 v104, v104, v105
	v_add_f32_e32 v252, v106, v252
	v_add_f32_e32 v253, v107, v253
	v_cvt_pk_bf16_f32 v105, v106, v107
	v_mfma_f32_32x32x16_bf16 v[32:47], v[168:171], v[112:115], v[32:47]
	v_exp_f32_e32 v84, v84
	v_exp_f32_e32 v85, v85
	v_exp_f32_e32 v86, v86
	v_exp_f32_e32 v87, v87
	v_add_f32_e32 v252, v108, v252
	v_add_f32_e32 v253, v109, v253
	v_cvt_pk_bf16_f32 v106, v108, v109
	v_add_f32_e32 v252, v110, v252
	v_add_f32_e32 v253, v111, v253
	v_cvt_pk_bf16_f32 v107, v110, v111
	v_mfma_f32_32x32x16_bf16 v[48:63], v[164:167], v[120:123], v[48:63]
	v_exp_f32_e32 v88, v88
	v_exp_f32_e32 v89, v89
	v_exp_f32_e32 v90, v90
	v_exp_f32_e32 v91, v91
	v_mfma_f32_32x32x16_bf16 v[32:47], v[160:163], v[120:123], v[32:47]
	v_exp_f32_e32 v92, v92
	v_exp_f32_e32 v93, v93
	v_exp_f32_e32 v94, v94
	v_exp_f32_e32 v95, v95
	s_cmp_eq_u32 s52, s4
	s_cbranch_scc0 .LBB0_82
.Lk0u_exit:
	v_add_f32_e32 v252, v80, v252
	v_add_f32_e32 v253, v81, v253
	v_cvt_pk_bf16_f32 v80, v80, v81
	v_add_f32_e32 v252, v82, v252
	v_add_f32_e32 v253, v83, v253
	v_cvt_pk_bf16_f32 v81, v82, v83
	v_add_f32_e32 v252, v84, v252
	v_add_f32_e32 v253, v85, v253
	v_cvt_pk_bf16_f32 v82, v84, v85
	v_add_f32_e32 v252, v86, v252
	v_add_f32_e32 v253, v87, v253
	v_cvt_pk_bf16_f32 v83, v86, v87
	v_add_f32_e32 v252, v88, v252
	v_add_f32_e32 v253, v89, v253
	v_cvt_pk_bf16_f32 v88, v88, v89
	v_add_f32_e32 v252, v90, v252
	v_add_f32_e32 v253, v91, v253
	v_cvt_pk_bf16_f32 v89, v90, v91
	v_add_f32_e32 v252, v92, v252
	v_add_f32_e32 v253, v93, v253
	v_cvt_pk_bf16_f32 v90, v92, v93
	v_add_f32_e32 v252, v94, v252
	v_add_f32_e32 v253, v95, v253
	v_cvt_pk_bf16_f32 v91, v94, v95
	v_add_f32_e32 v252, v252, v253
	v_add_f32_e32 v194, v194, v252
	v_mfma_f32_32x32x16_bf16 v[64:79], v[188:191], v[96:99], v[64:79]
	v_mfma_f32_32x32x16_bf16 v[16:31], v[184:187], v[96:99], v[16:31]
	v_mfma_f32_32x32x16_bf16 v[64:79], v[180:183], v[104:107], v[64:79]
	v_mfma_f32_32x32x16_bf16 v[16:31], v[176:179], v[104:107], v[16:31]
	v_mfma_f32_32x32x16_bf16 v[64:79], v[172:175], v[80:83], v[64:79]
	v_mfma_f32_32x32x16_bf16 v[16:31], v[168:171], v[80:83], v[16:31]
	v_mfma_f32_32x32x16_bf16 v[64:79], v[164:167], v[88:91], v[64:79]
	v_mfma_f32_32x32x16_bf16 v[16:31], v[160:163], v[88:91], v[16:31]
	s_lshl_b32 s4, s35, 14
	s_add_i32 s5, s4, 32
	v_add_u32_e32 v92, s5, v217
	v_add_u32_e32 v180, v92, v219
	v_add_u32_e32 v196, v92, v218
	v_add_u32_e32 v197, v92, v216
	v_add_u32_e32 v198, v92, v215
	s_waitcnt vmcnt(4)
	s_barrier
; #define MFMA(a, b, c) __builtin_amdgcn_mfma_f32_32x32x16_bf16((a), (b), (c), 0, 0, 0)
; #define KV_ISSUE(tile_, slot_) do { \
;     const bf16_t* kp_ = kbase + (size_t)(tile_) * 4096 + kvoff; const bf16_t* vp_ = vbase + (size_t)(tile_) * 4096 + kvoff; \
;     char* lp_ = smem + (slot_) * ATT_SLOT + tid * 16; \
;     dma16(kp_, lp_); dma16(kp_ + 2048, lp_ + 4096); dma16(vp_, lp_ + ATT_V); dma16(vp_ + 2048, lp_ + ATT_V + 4096); } while (0)
; template <int KIND>
; DI void attn_unit(const Params& p, int l, int b, int head, int qt, int qcol, int kcol, int vfeat, int gcol, int mixcol,
;                   int t1, int n1, int t2, int n2, char* smem) {
;     ...
;     for (int it = 0; it < nt; ++it) {
;         const int tile = (it < n1) ? t1 + it : t2 + (it - n1);
;         if (it + 1 < nt) asm volatile("s_waitcnt vmcnt(4)" ::: "memory"); else asm volatile("s_waitcnt vmcnt(0)" ::: "memory");
;         __builtin_amdgcn_s_barrier();
;         const char* sk = smem + sc * ATT_SLOT;
;         const char* sv = sk + ATT_V;
;         bool active = true;
;         if (KIND == 2 && tile < 32) active = (tile >= r0w) && (tile < r0w + 8);
;         bf16x8 kf[8], vf[8];
;         if (active) {
; #pragma unroll
;             for (int s = 0; s < 4; ++s)
; #pragma unroll
;                 for (int t = 0; t < 2; ++t) kf[2 * s + t] = *(const bf16x8*)(sk + (32 * t + r) * 128 + (((2 * s + h) ^ xr) << 4));
;         }
;         __builtin_amdgcn_sched_barrier(0);
;         if (it + 2 < nt) { const int nx = (it + 2 < n1) ? t1 + it + 2 : t2 + (it + 2 - n1); KV_ISSUE(nx, sn); }
;         sc = (sc == 2) ? 0 : sc + 1; sn = (sn == 2) ? 0 : sn + 1;
;         __builtin_amdgcn_sched_barrier(0);
;         if (active) {
;     ...
;             if (KIND == 0) {
;                 f32x16 S0[2], S1[2];
; #pragma unroll
;                 for (int t = 0; t < 2; ++t) { S0[t] = MFMA(kf[t], qf[0], cz); S1[t] = MFMA(kf[4 + t], qf[2], cz); }
; #pragma unroll
;                 for (int t = 0; t < 2; ++t) { S0[t] = MFMA(kf[2 + t], qf[1], S0[t]); S1[t] = MFMA(kf[6 + t], qf[3], S1[t]); }
;                 LOAD_VF();
;                 softmax_tile(S0, l0);
;                 pv_tile(S0, O0, vf);
;                 softmax_tile(S1, l1);
;                 pv_tile(S1, O1, vf);
	ds_read_b128 v[80:83], v180
	ds_read_b128 v[84:87], v180 offset:4096
	ds_read_b128 v[160:163], v196
	ds_read_b128 v[164:167], v196 offset:4096
	ds_read_b128 v[88:91], v197
	ds_read_b128 v[168:171], v197 offset:4096
	ds_read_b128 v[172:175], v198
	ds_read_b128 v[176:179], v198 offset:4096
	s_waitcnt lgkmcnt(0)
	v_mfma_f32_32x32x16_bf16 v[128:143], v[80:83], v[152:155], v[0:15]
	v_mfma_f32_32x32x16_bf16 v[96:111], v[88:91], v[156:159], v[0:15]
	v_mfma_f32_32x32x16_bf16 v[112:127], v[84:87], v[152:155], v[0:15]
	v_mfma_f32_32x32x16_bf16 v[80:95], v[168:171], v[156:159], v[0:15]
	v_mfma_f32_32x32x16_bf16 v[128:143], v[160:163], v[144:147], v[128:143]
	v_mfma_f32_32x32x16_bf16 v[96:111], v[172:175], v[148:151], v[96:111]
	v_mfma_f32_32x32x16_bf16 v[112:127], v[164:167], v[144:147], v[112:127]
	v_mfma_f32_32x32x16_bf16 v[80:95], v[176:179], v[148:151], v[80:95]
	ds_read_b128 v[188:191], v180 offset:8192
	ds_read_b128 v[184:187], v180 offset:12288
	ds_read_b128 v[180:183], v196 offset:8192
	ds_read_b128 v[176:179], v196 offset:12288
	ds_read_b128 v[172:175], v197 offset:8192
	ds_read_b128 v[168:171], v197 offset:12288
	ds_read_b128 v[164:167], v198 offset:8192
	ds_read_b128 v[160:163], v198 offset:12288
	s_nop 0
	v_exp_f32_e32 v128, v128
	v_exp_f32_e32 v129, v129
	v_exp_f32_e32 v130, v130
	v_exp_f32_e32 v131, v131
	v_exp_f32_e32 v132, v132
	v_exp_f32_e32 v133, v133
	v_exp_f32_e32 v134, v134
	v_exp_f32_e32 v135, v135
	v_add_f32_e64 v196, v128, 0
	v_add_f32_e64 v197, v129, 0
	v_cvt_pk_bf16_f32 v128, v128, v129
	v_add_f32_e64 v196, v130, v196
	v_add_f32_e64 v197, v131, v197
	v_cvt_pk_bf16_f32 v129, v130, v131
	v_cvt_pk_bf16_f32 v130, v132, v133
	v_cvt_pk_bf16_f32 v131, v134, v135
	v_add_f32_e64 v196, v132, v196
	v_add_f32_e64 v197, v133, v197
	v_exp_f32_e32 v136, v136
	s_waitcnt lgkmcnt(0)
	v_mfma_f32_32x32x16_bf16 v[48:63], v[188:191], v[128:131], v[48:63]
	v_exp_f32_e32 v137, v137
	v_exp_f32_e32 v138, v138
	v_exp_f32_e32 v139, v139
	v_exp_f32_e32 v132, v140
	v_exp_f32_e32 v133, v141
	v_exp_f32_e32 v140, v142
	v_exp_f32_e32 v141, v143
	v_mfma_f32_32x32x16_bf16 v[32:47], v[184:187], v[128:131], v[32:47]
	v_add_f32_e64 v134, v134, v196
	v_add_f32_e64 v135, v135, v197
	v_cvt_pk_bf16_f32 v128, v136, v137
	v_cvt_pk_bf16_f32 v129, v138, v139
	v_cvt_pk_bf16_f32 v130, v132, v133
	v_cvt_pk_bf16_f32 v131, v140, v141
	v_add_f32_e64 v134, v136, v134
	v_add_f32_e64 v135, v137, v135
	v_exp_f32_e32 v112, v112
	v_mfma_f32_32x32x16_bf16 v[48:63], v[180:183], v[128:131], v[48:63]
	v_add_f32_e64 v134, v138, v134
	v_add_f32_e64 v135, v139, v135
	v_exp_f32_e32 v113, v113
	v_add_f32_e64 v134, v132, v134
	v_add_f32_e64 v135, v133, v135
	v_exp_f32_e32 v116, v116
	v_add_f32_e64 v132, v140, v134
	v_add_f32_e64 v133, v141, v135
	v_exp_f32_e32 v134, v114
	v_exp_f32_e32 v135, v115
	v_mfma_f32_32x32x16_bf16 v[32:47], v[176:179], v[128:131], v[32:47]
	v_exp_f32_e32 v117, v117
	v_exp_f32_e32 v118, v118
	v_exp_f32_e32 v119, v119
	v_add_f32_e64 v132, v112, v132
	v_add_f32_e64 v133, v113, v133
	v_cvt_pk_bf16_f32 v112, v112, v113
	v_cvt_pk_bf16_f32 v113, v134, v135
	v_cvt_pk_bf16_f32 v114, v116, v117
	v_cvt_pk_bf16_f32 v115, v118, v119
	v_add_f32_e64 v128, v134, v132
	v_add_f32_e64 v129, v135, v133
	v_exp_f32_e32 v120, v120
	v_mfma_f32_32x32x16_bf16 v[48:63], v[172:175], v[112:115], v[48:63]
	v_add_f32_e64 v116, v116, v128
	v_add_f32_e64 v117, v117, v129
	v_exp_f32_e32 v121, v121
	v_add_f32_e64 v116, v118, v116
	v_add_f32_e64 v117, v119, v117
	v_exp_f32_e32 v118, v122
	v_exp_f32_e32 v119, v123
	v_exp_f32_e32 v122, v124
	v_exp_f32_e32 v123, v125
	v_mfma_f32_32x32x16_bf16 v[32:47], v[168:171], v[112:115], v[32:47]
	v_exp_f32_e32 v124, v126
	v_exp_f32_e32 v125, v127
	v_exp_f32_e32 v96, v96
	v_exp_f32_e32 v97, v97
	v_exp_f32_e32 v98, v98
	v_exp_f32_e32 v99, v99
	v_exp_f32_e32 v100, v100
	v_exp_f32_e32 v101, v101
	v_exp_f32_e32 v102, v102
	v_exp_f32_e32 v103, v103
	v_cvt_pk_bf16_f32 v112, v120, v121
	v_cvt_pk_bf16_f32 v113, v118, v119
	v_cvt_pk_bf16_f32 v114, v122, v123
	v_cvt_pk_bf16_f32 v115, v124, v125
	v_exp_f32_e32 v104, v104
	v_exp_f32_e32 v105, v105
	v_mfma_f32_32x32x16_bf16 v[48:63], v[164:167], v[112:115], v[48:63]
	v_exp_f32_e32 v106, v106
	v_exp_f32_e32 v107, v107
	v_exp_f32_e32 v80, v80
	v_exp_f32_e32 v81, v81
	v_exp_f32_e32 v82, v82
	v_exp_f32_e32 v83, v83
	v_exp_f32_e32 v84, v84
	v_mfma_f32_32x32x16_bf16 v[32:47], v[160:163], v[112:115], v[32:47]
	v_add_f32_e64 v112, v96, 0
	v_add_f32_e64 v113, v97, 0
	v_cvt_pk_bf16_f32 v96, v96, v97
	v_add_f32_e64 v112, v98, v112
	v_add_f32_e64 v113, v99, v113
	v_cvt_pk_bf16_f32 v97, v98, v99
	v_cvt_pk_bf16_f32 v98, v100, v101
	v_cvt_pk_bf16_f32 v99, v102, v103
	v_add_f32_e64 v112, v100, v112
	v_add_f32_e64 v113, v101, v113
	v_exp_f32_e32 v100, v108
	v_mfma_f32_32x32x16_bf16 v[64:79], v[188:191], v[96:99], v[64:79]
	v_exp_f32_e32 v101, v109
	v_add_f32_e64 v112, v102, v112
	v_add_f32_e64 v113, v103, v113
	v_exp_f32_e32 v102, v110
	v_exp_f32_e32 v103, v111
	v_add_f32_e64 v112, v104, v112
	v_add_f32_e64 v113, v105, v113
	v_exp_f32_e32 v85, v85
	v_add_f32_e64 v112, v106, v112
	v_add_f32_e64 v113, v107, v113
	v_mfma_f32_32x32x16_bf16 v[16:31], v[184:187], v[96:99], v[16:31]
	v_add_f32_e64 v108, v100, v112
	v_add_f32_e64 v109, v101, v113
	v_cvt_pk_bf16_f32 v98, v100, v101
	v_add_f32_e64 v96, v102, v108
	v_add_f32_e64 v97, v103, v109
	v_cvt_pk_bf16_f32 v99, v102, v103
	v_add_f32_e64 v108, v80, v96
	v_add_f32_e64 v109, v81, v97
	v_cvt_pk_bf16_f32 v96, v104, v105
	v_cvt_pk_bf16_f32 v97, v106, v107
	v_exp_f32_e32 v86, v86
	v_exp_f32_e32 v87, v87
	v_mfma_f32_32x32x16_bf16 v[64:79], v[180:183], v[96:99], v[64:79]
	v_add_f32_e64 v100, v82, v108
	v_add_f32_e64 v101, v83, v109
	v_exp_f32_e32 v88, v88
	v_add_f32_e64 v100, v84, v100
	v_add_f32_e64 v101, v85, v101
	v_exp_f32_e32 v89, v89
	v_cvt_pk_bf16_f32 v80, v80, v81
	v_cvt_pk_bf16_f32 v81, v82, v83
	v_cvt_pk_bf16_f32 v82, v84, v85
	v_mfma_f32_32x32x16_bf16 v[16:31], v[176:179], v[96:99], v[16:31]
	v_cvt_pk_bf16_f32 v83, v86, v87
	v_add_f32_e64 v96, v86, v100
	v_add_f32_e64 v97, v87, v101
	v_exp_f32_e32 v86, v90
	v_exp_f32_e32 v87, v91
	v_exp_f32_e32 v90, v92
	v_exp_f32_e32 v91, v93
	v_exp_f32_e32 v92, v94
	v_mfma_f32_32x32x16_bf16 v[64:79], v[172:175], v[80:83], v[64:79]
	v_exp_f32_e32 v93, v95
	s_addk_i32 s4, 0x4000
	v_add_f32_e64 v84, v88, v96
	v_add_f32_e64 v85, v89, v97
	s_cmp_lg_u32 s35, 2
	s_cselect_b32 s4, s4, 0
	s_add_i32 s4, s4, 32
	s_waitcnt vmcnt(0)
	v_mfma_f32_32x32x16_bf16 v[16:31], v[168:171], v[80:83], v[16:31]
	v_add_f32_e64 v80, v86, v84
	v_add_f32_e64 v81, v87, v85
	v_cvt_pk_bf16_f32 v82, v90, v91
	v_add_f32_e64 v80, v90, v80
	v_add_f32_e64 v81, v91, v81
	v_cvt_pk_bf16_f32 v83, v92, v93
	v_add_f32_e64 v168, v92, v80
	v_add_f32_e64 v169, v93, v81
	v_cvt_pk_bf16_f32 v80, v88, v89
	v_add_u32_e32 v88, s4, v217
	v_cvt_pk_bf16_f32 v81, v86, v87
	v_add_u32_e32 v174, v88, v219
	v_add_u32_e32 v175, v88, v218
	v_add_u32_e32 v176, v88, v216
	v_add_u32_e32 v177, v88, v215
	v_mfma_f32_32x32x16_bf16 v[64:79], v[164:167], v[80:83], v[64:79]
	s_barrier
; #define MFMA(a, b, c) __builtin_amdgcn_mfma_f32_32x32x16_bf16((a), (b), (c), 0, 0, 0)
; template <int KIND>
; DI void attn_unit(const Params& p, int l, int b, int head, int qt, int qcol, int kcol, int vfeat, int gcol, int mixcol,
;                   int t1, int n1, int t2, int n2, char* smem) {
;     ...
;     for (int it = 0; it < nt; ++it) {
;         const int tile = (it < n1) ? t1 + it : t2 + (it - n1);
;         if (it + 1 < nt) asm volatile("s_waitcnt vmcnt(4)" ::: "memory"); else asm volatile("s_waitcnt vmcnt(0)" ::: "memory");
;         __builtin_amdgcn_s_barrier();
;         const char* sk = smem + sc * ATT_SLOT;
;         const char* sv = sk + ATT_V;
;         bool active = true;
;         if (KIND == 2 && tile < 32) active = (tile >= r0w) && (tile < r0w + 8);
;         bf16x8 kf[8], vf[8];
;         if (active) {
; #pragma unroll
;             for (int s = 0; s < 4; ++s)
; #pragma unroll
;                 for (int t = 0; t < 2; ++t) kf[2 * s + t] = *(const bf16x8*)(sk + (32 * t + r) * 128 + (((2 * s + h) ^ xr) << 4));
;         }
;         __builtin_amdgcn_sched_barrier(0);
;         if (it + 2 < nt) { const int nx = (it + 2 < n1) ? t1 + it + 2 : t2 + (it + 2 - n1); KV_ISSUE(nx, sn); }
;         sc = (sc == 2) ? 0 : sc + 1; sn = (sn == 2) ? 0 : sn + 1;
;         __builtin_amdgcn_sched_barrier(0);
;         if (active) {
;     ...
;             if (KIND == 0) {
;                 f32x16 S0[2], S1[2];
; #pragma unroll
;                 for (int t = 0; t < 2; ++t) { S0[t] = MFMA(kf[t], qf[0], cz); S1[t] = MFMA(kf[4 + t], qf[2], cz); }
; #pragma unroll
;                 for (int t = 0; t < 2; ++t) { S0[t] = MFMA(kf[2 + t], qf[1], S0[t]); S1[t] = MFMA(kf[6 + t], qf[3], S1[t]); }
;                 LOAD_VF();
;                 softmax_tile(S0, l0);
;                 pv_tile(S0, O0, vf);
;                 softmax_tile(S1, l1);
;                 pv_tile(S1, O1, vf);
;     ...
;     l0 = xsum32(l0);
;     const float inv0 = 1.f / l0;
;     const int tid_e = otid();
;     const size_t qrow_e = (size_t)b * TPB + qt * 128 + 32 * (tid_e >> 6) + (tid_e & 31);
;     bf16_t* orow = p.hmix + ((size_t)(mixcol >> 5) * NTOK + qrow_e) * 32;
;     const bf16_t* grow = p.qkv + ((size_t)(gcol >> 6) * NTOK + qrow_e) * 64;
;     if (KIND == 0) {
;         l1 = xsum32(l1);
;         const float lam = p.lam[l];
;         const float inv1 = lam / l1;
	ds_read_b128 v[84:87], v174
	ds_read_b128 v[128:131], v174 offset:4096
	ds_read_b128 v[132:135], v175
	ds_read_b128 v[136:139], v175 offset:4096
	ds_read_b128 v[96:99], v176
	ds_read_b128 v[140:143], v176 offset:4096
	ds_read_b128 v[164:167], v177
	ds_read_b128 v[170:173], v177 offset:4096
	v_add_f32_e64 v116, v120, v116
	v_add_f32_e64 v117, v121, v117
	s_nop 0
	v_add_f32_e64 v116, v118, v116
	v_add_f32_e64 v117, v119, v117
	v_mfma_f32_32x32x16_bf16 v[16:31], v[160:163], v[80:83], v[16:31]
	v_add_f32_e64 v116, v122, v116
	v_add_f32_e64 v117, v123, v117
	v_add_f32_e64 v196, v124, v116
	v_add_f32_e64 v197, v125, v117
	s_waitcnt lgkmcnt(0)
	v_mfma_f32_32x32x16_bf16 v[112:127], v[84:87], v[152:155], v[0:15]
	v_mfma_f32_32x32x16_bf16 v[80:95], v[96:99], v[156:159], v[0:15]
	v_mfma_f32_32x32x16_bf16 v[96:111], v[128:131], v[152:155], v[0:15]
	v_mfma_f32_32x32x16_bf16 v[0:15], v[140:143], v[156:159], v[0:15]
	v_mfma_f32_32x32x16_bf16 v[112:127], v[132:135], v[144:147], v[112:127]
	v_mfma_f32_32x32x16_bf16 v[80:95], v[164:167], v[148:151], v[80:95]
	v_mfma_f32_32x32x16_bf16 v[96:111], v[136:139], v[144:147], v[96:111]
	v_mfma_f32_32x32x16_bf16 v[0:15], v[170:173], v[148:151], v[0:15]
	ds_read_b128 v[156:159], v174 offset:8192
	ds_read_b128 v[152:155], v174 offset:12288
	ds_read_b128 v[148:151], v175 offset:8192
	ds_read_b128 v[144:147], v175 offset:12288
	ds_read_b128 v[140:143], v176 offset:8192
	ds_read_b128 v[136:139], v176 offset:12288
	ds_read_b128 v[132:135], v177 offset:8192
	ds_read_b128 v[128:131], v177 offset:12288
	s_nop 0
	v_exp_f32_e32 v112, v112
	v_exp_f32_e32 v113, v113
	v_exp_f32_e32 v114, v114
	v_exp_f32_e32 v115, v115
	v_exp_f32_e32 v116, v116
	v_exp_f32_e32 v117, v117
	v_exp_f32_e32 v118, v118
	v_exp_f32_e32 v119, v119
	v_add_f32_e64 v160, v112, 0
	v_add_f32_e64 v161, v113, 0
	v_cvt_pk_bf16_f32 v112, v112, v113
	v_add_f32_e64 v160, v114, v160
	v_add_f32_e64 v161, v115, v161
	v_cvt_pk_bf16_f32 v113, v114, v115
	v_cvt_pk_bf16_f32 v114, v116, v117
	v_cvt_pk_bf16_f32 v115, v118, v119
	v_exp_f32_e32 v120, v120
	v_exp_f32_e32 v121, v121
	s_waitcnt lgkmcnt(0)
	v_mfma_f32_32x32x16_bf16 v[48:63], v[156:159], v[112:115], v[48:63]
	v_exp_f32_e32 v122, v122
	v_exp_f32_e32 v123, v123
	v_exp_f32_e32 v124, v124
	v_exp_f32_e32 v125, v125
	v_exp_f32_e32 v126, v126
	v_exp_f32_e32 v127, v127
	v_add_f32_e64 v160, v116, v160
	v_add_f32_e64 v161, v117, v161
	v_mfma_f32_32x32x16_bf16 v[32:47], v[152:155], v[112:115], v[32:47]
	v_add_f32_e64 v160, v118, v160
	v_add_f32_e64 v161, v119, v161
	v_exp_f32_e32 v118, v96
	v_add_f32_e64 v160, v120, v160
	v_add_f32_e64 v161, v121, v161
	v_exp_f32_e32 v119, v97
	v_add_f32_e64 v116, v122, v160
	v_add_f32_e64 v117, v123, v161
	v_exp_f32_e32 v160, v98
	v_exp_f32_e32 v161, v99
	v_cvt_pk_bf16_f32 v96, v120, v121
	v_cvt_pk_bf16_f32 v97, v122, v123
	v_cvt_pk_bf16_f32 v98, v124, v125
	v_cvt_pk_bf16_f32 v99, v126, v127
	v_add_f32_e64 v116, v124, v116
	v_add_f32_e64 v117, v125, v117
	v_exp_f32_e32 v100, v100
	v_mfma_f32_32x32x16_bf16 v[48:63], v[148:151], v[96:99], v[48:63]
	v_exp_f32_e32 v101, v101
	v_add_f32_e64 v116, v126, v116
	v_add_f32_e64 v117, v127, v117
	v_exp_f32_e32 v102, v102
	v_exp_f32_e32 v103, v103
	v_add_f32_e64 v112, v118, v116
	v_add_f32_e64 v113, v119, v117
	v_exp_f32_e32 v104, v104
	v_exp_f32_e32 v105, v105
	v_mfma_f32_32x32x16_bf16 v[32:47], v[144:147], v[96:99], v[32:47]
	v_add_f32_e64 v112, v160, v112
	v_add_f32_e64 v113, v161, v113
	v_exp_f32_e32 v106, v106
	v_exp_f32_e32 v107, v107
	v_add_f32_e64 v112, v100, v112
	v_add_f32_e64 v113, v101, v113
	v_exp_f32_e32 v108, v108
	v_add_f32_e64 v112, v102, v112
	v_add_f32_e64 v113, v103, v113
	v_cvt_pk_bf16_f32 v96, v118, v119
	v_cvt_pk_bf16_f32 v97, v160, v161
	v_cvt_pk_bf16_f32 v98, v100, v101
	v_cvt_pk_bf16_f32 v99, v102, v103
	v_exp_f32_e32 v109, v109
	v_exp_f32_e32 v100, v110
	v_mfma_f32_32x32x16_bf16 v[48:63], v[140:143], v[96:99], v[48:63]
	v_exp_f32_e32 v101, v111
	v_add_f32_e64 v102, v104, v112
	v_add_f32_e64 v103, v105, v113
	v_exp_f32_e32 v84, v84
	v_add_f32_e64 v102, v106, v102
	v_add_f32_e64 v103, v107, v103
	v_exp_f32_e32 v85, v85
	v_add_f32_e64 v102, v108, v102
	v_add_f32_e64 v103, v109, v103
	v_exp_f32_e32 v86, v86
	v_mfma_f32_32x32x16_bf16 v[32:47], v[136:139], v[96:99], v[32:47]
	v_cvt_pk_bf16_f32 v96, v104, v105
	v_exp_f32_e32 v104, v80
	v_exp_f32_e32 v105, v81
	v_cvt_pk_bf16_f32 v97, v106, v107
	v_exp_f32_e32 v106, v82
	v_exp_f32_e32 v107, v83
	v_exp_f32_e32 v87, v87
	v_add_f32_e64 v102, v100, v102
	v_add_f32_e64 v103, v101, v103
	v_add_f32_e64 v82, v104, 0
	v_add_f32_e64 v83, v105, 0
	v_exp_f32_e32 v88, v88
	v_exp_f32_e32 v89, v89
	v_mov_b32_e32 v110, v196
	v_mov_b32_e32 v111, v102
	v_mov_b32_e32 v102, v197
	v_add_f32_e64 v82, v106, v82
	v_add_f32_e64 v83, v107, v83
	v_exp_f32_e32 v90, v90
	v_exp_f32_e32 v91, v91
	v_cvt_pk_bf16_f32 v99, v100, v101
	v_add_f32_e64 v100, v110, v102
	v_add_f32_e64 v101, v111, v103
	v_add_f32_e64 v82, v84, v82
	v_add_f32_e64 v83, v85, v83
	v_exp_f32_e32 v92, v92
	v_exp_f32_e32 v93, v93
	s_add_u32 s7, s29, s7
	v_pk_add_f32 v[102:103], v[194:195], v[100:101] op_sel:[1,0] op_sel_hi:[0,1]
	v_add_f32_e64 v82, v86, v82
	v_add_f32_e64 v83, v87, v83
	s_addc_u32 s9, s9, 0
	s_add_i32 s8, s8, 0x36000
	s_lshl_b64 s[4:5], s[60:61], 2
	v_cvt_pk_bf16_f32 v98, v108, v109
	v_pk_add_f32 v[80:81], v[102:103], v[100:101] op_sel:[0,1] op_sel_hi:[1,0]
	v_add_f32_e64 v82, v88, v82
	v_add_f32_e64 v83, v89, v83
	s_add_u32 s4, s50, s4
	v_mfma_f32_32x32x16_bf16 v[48:63], v[132:135], v[96:99], v[48:63]
	v_mov_b32_e32 v81, v200
	s_addc_u32 s5, s51, s5
	v_cvt_pk_bf16_f32 v84, v84, v85
	v_cvt_pk_bf16_f32 v85, v86, v87
	v_exp_f32_e32 v94, v94
; DI int otid() { int t = threadIdx.x; asm volatile("" : "+v"(t)); return t; }
; DI float xsum32(float x) { const unsigned u = __float_as_uint(x); const auto r2 = __builtin_amdgcn_permlane32_swap(u, u, false, false); return __uint_as_float(r2[0]) + __uint_as_float(r2[1]); }
; template <int KIND>
; DI void attn_unit(const Params& p, int l, int b, int head, int qt, int qcol, int kcol, int vfeat, int gcol, int mixcol,
;                   int t1, int n1, int t2, int n2, char* smem) {
;     ...
;     l0 = xsum32(l0);
;     const float inv0 = 1.f / l0;
;     const int tid_e = otid();
;     const size_t qrow_e = (size_t)b * TPB + qt * 128 + 32 * (tid_e >> 6) + (tid_e & 31);
;     bf16_t* orow = p.hmix + ((size_t)(mixcol >> 5) * NTOK + qrow_e) * 32;
;     const bf16_t* grow = p.qkv + ((size_t)(gcol >> 6) * NTOK + qrow_e) * 64;
;     if (KIND == 0) {
;         l1 = xsum32(l1);
;         const float lam = p.lam[l];
;         const float inv1 = lam / l1;
;         float ss = 0.f;
; #pragma unroll
;         for (int t = 0; t < 2; ++t)
; #pragma unroll
;             for (int e = 0; e < 16; ++e) { const float o = O0[t][e] * inv0 - O1[t][e] * inv1; O0[t][e] = o; ss += o * o; }
;         ss = xsum32(ss);
;         const float rstd = rsqrtf(ss * (1.f / 64.f) + EPS) * p.lam[4 + l];
	v_exp_f32_e32 v95, v95
	v_mfma_f32_32x32x16_bf16 v[32:47], v[128:131], v[96:99], v[32:47]
	v_add_f32_e64 v96, v90, v82
	v_add_f32_e64 v97, v91, v83
	v_exp_f32_e32 v98, v0
	v_exp_f32_e32 v99, v1
	v_add_f32_e64 v0, v92, v96
	v_add_f32_e64 v1, v93, v97
	global_load_dword v96, v193, s[4:5]
	v_cvt_pk_bf16_f32 v82, v104, v105
	v_cvt_pk_bf16_f32 v83, v106, v107
	v_exp_f32_e32 v100, v2
	v_exp_f32_e32 v101, v3
	v_mfma_f32_32x32x16_bf16 v[64:79], v[156:159], v[82:85], v[64:79]
	v_exp_f32_e32 v86, v4
	v_exp_f32_e32 v87, v5
	v_cvt_pk_bf16_f32 v2, v88, v89
	v_cvt_pk_bf16_f32 v3, v90, v91
	v_cvt_pk_bf16_f32 v4, v92, v93
	v_cvt_pk_bf16_f32 v5, v94, v95
	v_add_f32_e64 v0, v94, v0
	v_add_f32_e64 v1, v95, v1
	v_mfma_f32_32x32x16_bf16 v[16:31], v[152:155], v[82:85], v[16:31]
	v_exp_f32_e32 v6, v6
	v_exp_f32_e32 v7, v7
	v_add_f32_e64 v0, v98, v0
	v_add_f32_e64 v1, v99, v1
	v_exp_f32_e32 v8, v8
	v_exp_f32_e32 v9, v9
	v_add_f32_e64 v0, v100, v0
	v_add_f32_e64 v1, v101, v1
	v_exp_f32_e32 v10, v10
	v_mfma_f32_32x32x16_bf16 v[64:79], v[148:151], v[2:5], v[64:79]
	v_exp_f32_e32 v11, v11
	v_add_f32_e64 v82, v86, v0
	v_add_f32_e64 v83, v87, v1
	v_exp_f32_e32 v12, v12
	v_exp_f32_e32 v13, v13
	v_add_f32_e64 v82, v6, v82
	v_add_f32_e64 v83, v7, v83
	v_ashrrev_i32_e32 v0, 1, v81
	v_and_b32_e32 v0, 0xffffffe0, v0
	v_mfma_f32_32x32x16_bf16 v[16:31], v[144:147], v[2:5], v[16:31]
	v_cvt_pk_bf16_f32 v5, v6, v7
	v_exp_f32_e32 v6, v14
	v_exp_f32_e32 v7, v15
	v_add_f32_e64 v14, v8, v82
	v_add_f32_e64 v15, v9, v83
	v_cvt_pk_bf16_f32 v2, v98, v99
	v_add_f32_e64 v14, v10, v14
	v_add_f32_e64 v15, v11, v15
	v_cvt_pk_bf16_f32 v3, v100, v101
	v_cvt_pk_bf16_f32 v4, v86, v87
	v_add_f32_e64 v14, v12, v14
	v_add_f32_e64 v15, v13, v15
	v_ashrrev_i32_e32 v1, 31, v0
	v_mfma_f32_32x32x16_bf16 v[64:79], v[140:143], v[2:5], v[64:79]
	v_add_f32_e64 v14, v6, v14
	v_add_f32_e64 v15, v7, v15
	v_and_or_b32 v84, v81, 31, s7
	v_mov_b32_e32 v85, s9
	v_lshl_add_u64 v[84:85], v[84:85], 0, v[0:1]
	s_mov_b32 s9, s75
	v_lshl_add_u64 v[0:1], v[84:85], 0, s[8:9]
	v_mov_b32_e32 v82, v168
	v_mfma_f32_32x32x16_bf16 v[16:31], v[136:139], v[2:5], v[16:31]
	v_cvt_pk_bf16_f32 v5, v6, v7
	v_mov_b32_e32 v6, v80
	s_nop 1
	v_permlane32_swap_b32_e32 v80, v6
	v_cvt_pk_bf16_f32 v2, v8, v9
	v_add_f32_e32 v8, v80, v6
	v_div_scale_f32 v9, s[8:9], v8, v8, 1.0
	v_cvt_pk_bf16_f32 v3, v10, v11
	v_rcp_f32_e32 v10, v9
	v_cvt_pk_bf16_f32 v4, v12, v13
	v_mov_b32_e32 v83, v14
	v_mov_b32_e32 v14, v169
	v_mfma_f32_32x32x16_bf16 v[64:79], v[132:135], v[2:5], v[64:79]
	v_add_f32_e64 v14, v82, v14
	v_add_f32_e64 v15, v83, v15
	global_load_dword v80, v193, s[4:5] offset:16
	v_add_f32_e64 v6, v194, v14
	v_add_f32_e64 v7, v195, v15
	v_lshlrev_b64 v[0:1], 7, v[0:1]
	v_pk_add_f32 v[6:7], v[6:7], v[14:15] op_sel:[0,1] op_sel_hi:[1,0]
	v_lshl_add_u64 v[0:1], s[40:41], 0, v[0:1]
	v_lshlrev_b32_e32 v88, 3, v214
	v_mfma_f32_32x32x16_bf16 v[16:31], v[128:131], v[2:5], v[16:31]
	v_fma_f32 v2, -v9, v10, 1.0
	v_fmac_f32_e32 v10, v2, v10
	v_div_scale_f32 v2, vcc, 1.0, v8, 1.0
	v_mul_f32_e32 v3, v2, v10
	v_fma_f32 v4, -v9, v3, v2
	v_fmac_f32_e32 v3, v4, v10
	v_fma_f32 v2, -v9, v3, v2
	v_div_fmas_f32 v2, v2, v10, v3
	v_div_fixup_f32 v8, v2, v8, 1.0
	v_mov_b32_e32 v2, v6
	s_nop 1
	v_permlane32_swap_b32_e32 v6, v2
	v_add_f32_e32 v4, v6, v2
	s_waitcnt vmcnt(0)
	v_div_scale_f32 v5, s[4:5], v4, v4, v96
	v_rcp_f32_e32 v6, v5
	v_mov_b32_e32 v89, v193
	v_lshl_add_u64 v[0:1], v[0:1], 0, v[88:89]
	s_mul_i32 s6, s6, 0x9000
	v_fma_f32 v7, -v5, v6, 1.0
	s_mov_b32 s7, s75
	v_fmac_f32_e32 v6, v7, v6
	v_div_scale_f32 v7, vcc, v96, v4, v96
	global_load_dwordx2 v[90:91], v[0:1], off
	v_lshl_add_u64 v[2:3], v[84:85], 0, s[6:7]
	v_mul_f32_e32 v9, v7, v6
	s_load_dwordx2 s[4:5], s[0:1], 0xb8
	s_load_dwordx2 s[6:7], s[0:1], 0x78
	v_fma_f32 v10, -v5, v9, v7
	v_fmac_f32_e32 v9, v10, v6
	v_fma_f32 v5, -v5, v9, v7
	v_lshlrev_b64 v[2:3], 6, v[2:3]
	v_div_fmas_f32 v5, v5, v6, v9
	v_div_fixup_f32 v10, v5, v4, v96
	s_waitcnt lgkmcnt(0)
	v_lshl_add_u64 v[2:3], s[4:5], 0, v[2:3]
	s_add_u32 s4, s6, s46
	s_addc_u32 s5, s7, s47
	v_pk_mul_f32 v[4:5], v[66:67], v[10:11] op_sel_hi:[1,0]
	v_pk_mul_f32 v[16:17], v[16:17], v[10:11] op_sel_hi:[1,0]
	v_pk_fma_f32 v[14:15], v[50:51], v[8:9], v[4:5] op_sel_hi:[1,0,1] neg_lo:[0,0,1] neg_hi:[0,0,1]
	global_load_dwordx4 v[4:7], v192, s[4:5]
	v_pk_mul_f32 v[50:51], v[64:65], v[10:11] op_sel_hi:[1,0]
	v_mul_f32_e32 v64, v15, v15
	v_pk_fma_f32 v[48:49], v[48:49], v[8:9], v[50:51] op_sel_hi:[1,0,1] neg_lo:[0,0,1] neg_hi:[0,0,1]
	v_pk_mul_f32 v[18:19], v[18:19], v[10:11] op_sel_hi:[1,0]
	v_mul_f32_e32 v50, v49, v49
	v_pk_fma_f32 v[50:51], v[48:49], v[48:49], v[50:51] op_sel_hi:[1,1,0]
	v_pk_fma_f32 v[16:17], v[32:33], v[8:9], v[16:17] op_sel_hi:[1,0,1] neg_lo:[0,0,1] neg_hi:[0,0,1]
	v_pk_fma_f32 v[50:51], v[14:15], v[14:15], v[50:51]
	v_pk_fma_f32 v[18:19], v[34:35], v[8:9], v[18:19] op_sel_hi:[1,0,1] neg_lo:[0,0,1] neg_hi:[0,0,1]
	v_pk_add_f32 v[50:51], v[64:65], v[50:51] op_sel_hi:[0,1]
	v_pk_mul_f32 v[64:65], v[70:71], v[10:11] op_sel_hi:[1,0]
	v_mul_f32_e32 v34, v17, v17
	v_pk_fma_f32 v[54:55], v[54:55], v[8:9], v[64:65] op_sel_hi:[1,0,1] neg_lo:[0,0,1] neg_hi:[0,0,1]
	v_pk_mul_f32 v[64:65], v[68:69], v[10:11] op_sel_hi:[1,0]
	v_pk_mul_f32 v[20:21], v[20:21], v[10:11] op_sel_hi:[1,0]
	v_pk_fma_f32 v[52:53], v[52:53], v[8:9], v[64:65] op_sel_hi:[1,0,1] neg_lo:[0,0,1] neg_hi:[0,0,1]
	v_pk_fma_f32 v[20:21], v[36:37], v[8:9], v[20:21] op_sel_hi:[1,0,1] neg_lo:[0,0,1] neg_hi:[0,0,1]
	v_pk_fma_f32 v[50:51], v[52:53], v[52:53], v[50:51]
	v_mul_f32_e32 v64, v53, v53
	v_pk_add_f32 v[50:51], v[64:65], v[50:51] op_sel_hi:[0,1]
	v_pk_fma_f32 v[50:51], v[54:55], v[54:55], v[50:51]
; DI unsigned pk2(float a, float b) { f2_t v = {a, b}; bf2_t r = __builtin_convertvector(v, bf2_t); return __builtin_bit_cast(unsigned, r); }
; DI float bf2f(bf16_t v) { return __uint_as_float(((unsigned)v) << 16); }
; DI float xsum32(float x) { const unsigned u = __float_as_uint(x); const auto r2 = __builtin_amdgcn_permlane32_swap(u, u, false, false); return __uint_as_float(r2[0]) + __uint_as_float(r2[1]); }
; template <int KIND>
; DI void attn_unit(const Params& p, int l, int b, int head, int qt, int qcol, int kcol, int vfeat, int gcol, int mixcol,
;                   int t1, int n1, int t2, int n2, char* smem) {
;     ...
;         float ss = 0.f;
; #pragma unroll
;         for (int t = 0; t < 2; ++t)
; #pragma unroll
;             for (int e = 0; e < 16; ++e) { const float o = O0[t][e] * inv0 - O1[t][e] * inv1; O0[t][e] = o; ss += o * o; }
;         ss = xsum32(ss);
;         const float rstd = rsqrtf(ss * (1.f / 64.f) + EPS) * p.lam[4 + l];
;         const float* sw = p.subln + l * 64;
; #pragma unroll
;         for (int t = 0; t < 2; ++t)
; #pragma unroll
;             for (int q = 0; q < 4; ++q) {
;                 const int f = 32 * t + 8 * q + 4 * h;
;                 const float4 w4 = *(const float4*)(sw + f);
;                 const uint2 gg = *(const uint2*)(grow + f);
;                 const float g0 = bf2f((bf16_t)(gg.x & 0xffff)), g1 = bf2f((bf16_t)(gg.x >> 16)), g2 = bf2f((bf16_t)(gg.y & 0xffff)), g3 = bf2f((bf16_t)(gg.y >> 16));
;                 uint2 o;
;                 o.x = pk2(O0[t][4 * q + 0] * rstd * w4.x * g0, O0[t][4 * q + 1] * rstd * w4.y * g1);
;                 o.y = pk2(O0[t][4 * q + 2] * rstd * w4.z * g2, O0[t][4 * q + 3] * rstd * w4.w * g3);
;                 *(uint2*)(orow + (size_t)t * NTOK * 32 + 8 * q + 4 * h) = o;
;             }
	v_mul_f32_e32 v64, v55, v55
	v_pk_add_f32 v[50:51], v[64:65], v[50:51] op_sel_hi:[0,1]
	v_pk_mul_f32 v[64:65], v[74:75], v[10:11] op_sel_hi:[1,0]
	v_pk_mul_f32 v[22:23], v[22:23], v[10:11] op_sel_hi:[1,0]
	v_pk_fma_f32 v[58:59], v[58:59], v[8:9], v[64:65] op_sel_hi:[1,0,1] neg_lo:[0,0,1] neg_hi:[0,0,1]
	v_pk_mul_f32 v[64:65], v[72:73], v[10:11] op_sel_hi:[1,0]
	v_pk_fma_f32 v[22:23], v[38:39], v[8:9], v[22:23] op_sel_hi:[1,0,1] neg_lo:[0,0,1] neg_hi:[0,0,1]
	v_pk_fma_f32 v[56:57], v[56:57], v[8:9], v[64:65] op_sel_hi:[1,0,1] neg_lo:[0,0,1] neg_hi:[0,0,1]
	v_pk_mul_f32 v[24:25], v[24:25], v[10:11] op_sel_hi:[1,0]
	v_pk_fma_f32 v[50:51], v[56:57], v[56:57], v[50:51]
	v_mul_f32_e32 v64, v57, v57
	v_pk_add_f32 v[50:51], v[64:65], v[50:51] op_sel_hi:[0,1]
	v_pk_fma_f32 v[50:51], v[58:59], v[58:59], v[50:51]
	v_mul_f32_e32 v64, v59, v59
	v_pk_add_f32 v[50:51], v[64:65], v[50:51] op_sel_hi:[0,1]
	v_pk_mul_f32 v[64:65], v[78:79], v[10:11] op_sel_hi:[1,0]
	v_pk_fma_f32 v[24:25], v[40:41], v[8:9], v[24:25] op_sel_hi:[1,0,1] neg_lo:[0,0,1] neg_hi:[0,0,1]
	v_pk_fma_f32 v[62:63], v[62:63], v[8:9], v[64:65] op_sel_hi:[1,0,1] neg_lo:[0,0,1] neg_hi:[0,0,1]
	v_pk_mul_f32 v[64:65], v[76:77], v[10:11] op_sel_hi:[1,0]
	v_pk_mul_f32 v[26:27], v[26:27], v[10:11] op_sel_hi:[1,0]
	v_pk_fma_f32 v[60:61], v[60:61], v[8:9], v[64:65] op_sel_hi:[1,0,1] neg_lo:[0,0,1] neg_hi:[0,0,1]
	v_pk_fma_f32 v[26:27], v[42:43], v[8:9], v[26:27] op_sel_hi:[1,0,1] neg_lo:[0,0,1] neg_hi:[0,0,1]
	v_pk_fma_f32 v[50:51], v[60:61], v[60:61], v[50:51]
	v_mul_f32_e32 v64, v61, v61
	v_pk_add_f32 v[50:51], v[64:65], v[50:51] op_sel_hi:[0,1]
	v_pk_fma_f32 v[50:51], v[62:63], v[62:63], v[50:51]
	v_mul_f32_e32 v64, v63, v63
	v_pk_add_f32 v[50:51], v[64:65], v[50:51] op_sel_hi:[0,1]
	v_pk_fma_f32 v[32:33], v[16:17], v[16:17], v[50:51]
	v_pk_mul_f32 v[30:31], v[30:31], v[10:11] op_sel_hi:[1,0]
	v_pk_add_f32 v[32:33], v[34:35], v[32:33] op_sel_hi:[0,1]
	v_pk_fma_f32 v[32:33], v[18:19], v[18:19], v[32:33]
	v_mul_f32_e32 v34, v19, v19
	v_pk_add_f32 v[32:33], v[34:35], v[32:33] op_sel_hi:[0,1]
	v_pk_fma_f32 v[32:33], v[20:21], v[20:21], v[32:33]
	v_mul_f32_e32 v34, v21, v21
	v_pk_add_f32 v[32:33], v[34:35], v[32:33] op_sel_hi:[0,1]
	v_pk_fma_f32 v[32:33], v[22:23], v[22:23], v[32:33]
	v_mul_f32_e32 v34, v23, v23
	v_pk_add_f32 v[32:33], v[34:35], v[32:33] op_sel_hi:[0,1]
	v_pk_fma_f32 v[32:33], v[24:25], v[24:25], v[32:33]
	v_mul_f32_e32 v34, v25, v25
	v_pk_add_f32 v[32:33], v[34:35], v[32:33] op_sel_hi:[0,1]
	v_pk_fma_f32 v[32:33], v[26:27], v[26:27], v[32:33]
	v_mul_f32_e32 v34, v27, v27
	v_pk_mul_f32 v[10:11], v[28:29], v[10:11] op_sel_hi:[1,0]
	v_pk_add_f32 v[32:33], v[34:35], v[32:33] op_sel_hi:[0,1]
	v_pk_fma_f32 v[30:31], v[46:47], v[8:9], v[30:31] op_sel_hi:[1,0,1] neg_lo:[0,0,1] neg_hi:[0,0,1]
	v_pk_fma_f32 v[8:9], v[44:45], v[8:9], v[10:11] op_sel_hi:[1,0,1] neg_lo:[0,0,1] neg_hi:[0,0,1]
	s_waitcnt vmcnt(1)
	v_lshlrev_b32_e32 v12, 16, v90
	v_pk_fma_f32 v[10:11], v[8:9], v[8:9], v[32:33]
	v_mul_f32_e32 v28, v9, v9
	v_pk_add_f32 v[10:11], v[28:29], v[10:11] op_sel_hi:[0,1]
	v_pk_fma_f32 v[10:11], v[30:31], v[30:31], v[10:11]
	v_mul_f32_e32 v28, v31, v31
	v_pk_add_f32 v[10:11], v[28:29], v[10:11] op_sel_hi:[0,1]
	v_mov_b32_e32 v11, v10
	s_nop 1
	v_permlane32_swap_b32_e32 v10, v11
	v_add_f32_e32 v10, v10, v11
	v_fmamk_f32 v10, v10, 0x3c800000, v201
	v_mul_f32_e32 v11, 0x4b800000, v10
	v_cmp_gt_f32_e32 vcc, s87, v10
	v_and_b32_e32 v13, 0xffff0000, v90
	v_lshl_add_u64 v[2:3], v[2:3], 0, v[88:89]
	v_cndmask_b32_e32 v10, v10, v11, vcc
	v_rsq_f32_e32 v28, v10
	v_lshlrev_b32_e32 v10, 16, v91
	v_and_b32_e32 v11, 0xffff0000, v91
	s_mov_b32 s6, 0x120000
	v_mul_f32_e32 v29, 0x45800000, v28
	v_cndmask_b32_e32 v28, v28, v29, vcc
	v_mul_f32_e32 v28, v80, v28
	v_pk_mul_f32 v[32:33], v[48:49], v[28:29] op_sel_hi:[1,0]
	s_waitcnt vmcnt(0)
	v_pk_mul_f32 v[4:5], v[4:5], v[32:33]
	s_nop 0
	v_pk_mul_f32 v[4:5], v[4:5], v[12:13]
	v_pk_mul_f32 v[12:13], v[14:15], v[28:29] op_sel_hi:[1,0]
	v_cvt_pk_bf16_f32 v4, v4, v5
	v_pk_mul_f32 v[6:7], v[6:7], v[12:13]
	v_pk_mul_f32 v[14:15], v[52:53], v[28:29] op_sel_hi:[1,0]
	v_pk_mul_f32 v[6:7], v[6:7], v[10:11]
	s_nop 0
	v_cvt_pk_bf16_f32 v5, v6, v7
	global_store_dwordx2 v[2:3], v[4:5], off
	global_load_dwordx2 v[10:11], v[0:1], off offset:16
	s_nop 0
	global_load_dwordx4 v[4:7], v192, s[4:5] offset:32
	s_waitcnt vmcnt(1)
	v_lshlrev_b32_e32 v12, 16, v10
	v_and_b32_e32 v13, 0xffff0000, v10
	s_waitcnt vmcnt(0)
; DI unsigned pk2(float a, float b) { f2_t v = {a, b}; bf2_t r = __builtin_convertvector(v, bf2_t); return __builtin_bit_cast(unsigned, r); }
; DI float bf2f(bf16_t v) { return __uint_as_float(((unsigned)v) << 16); }
; template <int KIND>
; DI void attn_unit(const Params& p, int l, int b, int head, int qt, int qcol, int kcol, int vfeat, int gcol, int mixcol,
;                   int t1, int n1, int t2, int n2, char* smem) {
;     ...
;         const float* sw = p.subln + l * 64;
; #pragma unroll
;         for (int t = 0; t < 2; ++t)
; #pragma unroll
;             for (int q = 0; q < 4; ++q) {
;                 const int f = 32 * t + 8 * q + 4 * h;
;                 const float4 w4 = *(const float4*)(sw + f);
;                 const uint2 gg = *(const uint2*)(grow + f);
;                 const float g0 = bf2f((bf16_t)(gg.x & 0xffff)), g1 = bf2f((bf16_t)(gg.x >> 16)), g2 = bf2f((bf16_t)(gg.y & 0xffff)), g3 = bf2f((bf16_t)(gg.y >> 16));
;                 uint2 o;
;                 o.x = pk2(O0[t][4 * q + 0] * rstd * w4.x * g0, O0[t][4 * q + 1] * rstd * w4.y * g1);
;                 o.y = pk2(O0[t][4 * q + 2] * rstd * w4.z * g2, O0[t][4 * q + 3] * rstd * w4.w * g3);
;                 *(uint2*)(orow + (size_t)t * NTOK * 32 + 8 * q + 4 * h) = o;
;             }
	v_pk_mul_f32 v[4:5], v[4:5], v[14:15]
	v_lshlrev_b32_e32 v10, 16, v11
	v_pk_mul_f32 v[4:5], v[4:5], v[12:13]
	v_pk_mul_f32 v[12:13], v[54:55], v[28:29] op_sel_hi:[1,0]
	v_and_b32_e32 v11, 0xffff0000, v11
	v_pk_mul_f32 v[6:7], v[12:13], v[6:7]
	v_cvt_pk_bf16_f32 v4, v4, v5
	v_pk_mul_f32 v[6:7], v[6:7], v[10:11]
	v_pk_mul_f32 v[14:15], v[56:57], v[28:29] op_sel_hi:[1,0]
	v_cvt_pk_bf16_f32 v5, v6, v7
	global_store_dwordx2 v[2:3], v[4:5], off offset:16
	global_load_dwordx2 v[10:11], v[0:1], off offset:32
	s_nop 0
	global_load_dwordx4 v[4:7], v192, s[4:5] offset:64
	s_waitcnt vmcnt(1)
	v_lshlrev_b32_e32 v12, 16, v10
	v_and_b32_e32 v13, 0xffff0000, v10
	s_waitcnt vmcnt(0)
	v_pk_mul_f32 v[4:5], v[14:15], v[4:5]
	v_lshlrev_b32_e32 v10, 16, v11
	v_pk_mul_f32 v[4:5], v[4:5], v[12:13]
	v_pk_mul_f32 v[12:13], v[58:59], v[28:29] op_sel_hi:[1,0]
	v_and_b32_e32 v11, 0xffff0000, v11
	v_pk_mul_f32 v[6:7], v[12:13], v[6:7]
	v_cvt_pk_bf16_f32 v4, v4, v5
	v_pk_mul_f32 v[6:7], v[6:7], v[10:11]
	v_pk_mul_f32 v[12:13], v[60:61], v[28:29] op_sel_hi:[1,0]
	v_cvt_pk_bf16_f32 v5, v6, v7
	global_store_dwordx2 v[2:3], v[4:5], off offset:32
	global_load_dwordx2 v[10:11], v[0:1], off offset:48
	s_nop 0
	global_load_dwordx4 v[4:7], v192, s[4:5] offset:96
	v_pk_mul_f32 v[14:15], v[62:63], v[28:29] op_sel_hi:[1,0]
	s_waitcnt vmcnt(1)
	v_lshlrev_b32_e32 v32, 16, v10
	v_and_b32_e32 v33, 0xffff0000, v10
	v_lshlrev_b32_e32 v10, 16, v11
	v_and_b32_e32 v11, 0xffff0000, v11
	s_waitcnt vmcnt(0)
	v_pk_mul_f32 v[4:5], v[12:13], v[4:5]
	v_pk_mul_f32 v[6:7], v[14:15], v[6:7]
	v_pk_mul_f32 v[4:5], v[4:5], v[32:33]
	v_pk_mul_f32 v[6:7], v[6:7], v[10:11]
	v_cvt_pk_bf16_f32 v4, v4, v5
	v_cvt_pk_bf16_f32 v5, v6, v7
	global_store_dwordx2 v[2:3], v[4:5], off offset:48
	global_load_dwordx2 v[10:11], v[0:1], off offset:64
	s_nop 0
	global_load_dwordx4 v[4:7], v192, s[4:5] offset:128
	v_add_co_u32_e32 v12, vcc, s6, v2
	v_pk_mul_f32 v[14:15], v[18:19], v[28:29] op_sel_hi:[1,0]
	s_nop 0
	v_addc_co_u32_e32 v13, vcc, 0, v3, vcc
	v_pk_mul_f32 v[2:3], v[16:17], v[28:29] op_sel_hi:[1,0]
	s_waitcnt vmcnt(1)
	v_lshlrev_b32_e32 v16, 16, v10
	v_and_b32_e32 v17, 0xffff0000, v10
	v_lshlrev_b32_e32 v10, 16, v11
	v_and_b32_e32 v11, 0xffff0000, v11
	s_waitcnt vmcnt(0)
	v_pk_mul_f32 v[2:3], v[2:3], v[4:5]
	v_pk_mul_f32 v[4:5], v[14:15], v[6:7]
	v_pk_mul_f32 v[2:3], v[2:3], v[16:17]
	v_pk_mul_f32 v[4:5], v[4:5], v[10:11]
	v_cvt_pk_bf16_f32 v2, v2, v3
	v_cvt_pk_bf16_f32 v3, v4, v5
	global_store_dwordx2 v[12:13], v[2:3], off
	global_load_dwordx2 v[6:7], v[0:1], off offset:80
	s_nop 0
	global_load_dwordx4 v[2:5], v192, s[4:5] offset:160
	v_pk_mul_f32 v[10:11], v[20:21], v[28:29] op_sel_hi:[1,0]
	v_pk_mul_f32 v[14:15], v[22:23], v[28:29] op_sel_hi:[1,0]
	s_waitcnt vmcnt(1)
	v_lshlrev_b32_e32 v16, 16, v6
	v_and_b32_e32 v17, 0xffff0000, v6
	v_lshlrev_b32_e32 v6, 16, v7
	v_and_b32_e32 v7, 0xffff0000, v7
	s_waitcnt vmcnt(0)
	v_pk_mul_f32 v[2:3], v[10:11], v[2:3]
	v_pk_mul_f32 v[4:5], v[14:15], v[4:5]
	v_pk_mul_f32 v[2:3], v[2:3], v[16:17]
	v_pk_mul_f32 v[4:5], v[4:5], v[6:7]
	v_cvt_pk_bf16_f32 v2, v2, v3
	v_cvt_pk_bf16_f32 v3, v4, v5
	global_store_dwordx2 v[12:13], v[2:3], off offset:16
	global_load_dwordx2 v[6:7], v[0:1], off offset:96
	s_nop 0
	global_load_dwordx4 v[2:5], v192, s[4:5] offset:192
	v_pk_mul_f32 v[10:11], v[24:25], v[28:29] op_sel_hi:[1,0]
	v_pk_mul_f32 v[14:15], v[26:27], v[28:29] op_sel_hi:[1,0]
	s_waitcnt vmcnt(1)
	v_lshlrev_b32_e32 v16, 16, v6
	v_and_b32_e32 v17, 0xffff0000, v6
	v_lshlrev_b32_e32 v6, 16, v7
	v_and_b32_e32 v7, 0xffff0000, v7
	s_waitcnt vmcnt(0)
	v_pk_mul_f32 v[2:3], v[10:11], v[2:3]
	v_pk_mul_f32 v[4:5], v[14:15], v[4:5]
	v_pk_mul_f32 v[2:3], v[2:3], v[16:17]
	v_pk_mul_f32 v[4:5], v[4:5], v[6:7]
	v_cvt_pk_bf16_f32 v2, v2, v3
	v_cvt_pk_bf16_f32 v3, v4, v5
	global_store_dwordx2 v[12:13], v[2:3], off offset:32
	global_load_dwordx2 v[4:5], v[0:1], off offset:112
	s_nop 0
	global_load_dwordx4 v[0:3], v192, s[4:5] offset:224
	v_pk_mul_f32 v[6:7], v[8:9], v[28:29] op_sel_hi:[1,0]
	v_pk_mul_f32 v[8:9], v[30:31], v[28:29] op_sel_hi:[1,0]
	s_mov_b64 s[4:5], 0
	s_waitcnt vmcnt(1)
	v_lshlrev_b32_e32 v10, 16, v4
	v_and_b32_e32 v11, 0xffff0000, v4
	v_lshlrev_b32_e32 v4, 16, v5
	v_and_b32_e32 v5, 0xffff0000, v5
	s_waitcnt vmcnt(0)
	v_pk_mul_f32 v[0:1], v[6:7], v[0:1]
	v_pk_mul_f32 v[2:3], v[8:9], v[2:3]
	v_pk_mul_f32 v[0:1], v[0:1], v[10:11]
	v_pk_mul_f32 v[2:3], v[2:3], v[4:5]
	v_cvt_pk_bf16_f32 v0, v0, v1
	v_cvt_pk_bf16_f32 v1, v2, v3
	global_store_dwordx2 v[12:13], v[0:1], off offset:48
	s_branch .LBB0_71
